# v98 + dense QKV epilogue and residual-epilogue chunk 0: packed f32 mul/add/fma emitted as scalar pairs (432 sites)
# baseline (speedup 1.0000x reference)
.LBB0_773:
	s_lshl_b32 s4, s4, 10
	s_add_i32 s4, s4, 0
	s_lshl_b32 s6, s7, 8
	s_add_i32 s97, s4, s6
	s_add_i32 s97, s97, 0x20000
	v_mov_b32_e32 v179, v175
	v_mov_b32_e32 v157, v135
	v_lshl_add_u32 v156, v179, 2, s97
	ds_read_b32 v170, v156
	v_mov_b32_e32 v135, v131
	s_lshl_b32 s94, s7, 6
	s_lshl_b32 s66, s5, 8
	v_mov_b32_e32 v156, v130
	s_waitcnt lgkmcnt(0)
	v_mul_f32_e32 v168, v134, v170
	v_mul_f32_e32 v169, v135, v170
	v_mov_b32_e32 v134, v132
	v_mov_b32_e32 v135, v137
	v_mul_f32_e32 v162, v134, v170
	v_mul_f32_e32 v163, v135, v170
	v_mov_b32_e32 v135, v127
	v_mov_b32_e32 v127, v123
	v_mov_b32_e32 v137, v133
	v_mul_f32_e32 v160, v126, v170
	v_mul_f32_e32 v161, v127, v170
	v_mov_b32_e32 v126, v124
	v_mov_b32_e32 v127, v129
	v_mov_b32_e32 v129, v125
	s_add_i32 s4, s94, s66
	v_mul_f32_e32 v166, v156, v170
	v_mul_f32_e32 v167, v157, v170
	v_mul_f32_e32 v164, v136, v170
	v_mul_f32_e32 v165, v137, v170
	v_mov_b32_e32 v134, v122
	v_mul_f32_e32 v136, v126, v170
	v_mul_f32_e32 v137, v127, v170
	v_mul_f32_e32 v156, v128, v170
	v_mul_f32_e32 v157, v129, v170
	v_cndmask_b32_e64 v126, 0, 1, s[82:83]
	v_lshlrev_b32_e32 v177, 2, v178
	v_add_u32_e32 v180, s4, v179
	v_mul_f32_e32 v158, v134, v170
	v_mul_f32_e32 v159, v135, v170
	v_cmp_ne_u32_e64 s[40:41], 1, v126
	s_andn2_b64 vcc, exec, s[82:83]
	v_pk_mov_b32 v[134:135], v[136:137], v[156:157] op_sel:[1,0]
	s_cbranch_vccnz .LBB0_775
	v_mul_f32_e32 v122, v168, v168
	v_mul_f32_e32 v123, v169, v169
	v_mul_f32_e32 v124, v166, v166
	v_mul_f32_e32 v125, v167, v167
	v_mul_f32_e32 v126, v164, v164
	v_mul_f32_e32 v127, v165, v165
	v_add_f32_e32 v122, v122, v125
	v_mul_f32_e32 v128, v162, v162
	v_mul_f32_e32 v129, v163, v163
	v_add_f32_e32 v122, v126, v122
	v_add_f32_e32 v122, v129, v122
	v_add_f32_e32 v122, v124, v122
	v_add_f32_e32 v122, v123, v122
	v_add_f32_e32 v122, v128, v122
	v_add_f32_e32 v122, v127, v122
	v_fmac_f32_e32 v122, v160, v160
	v_mul_f32_e32 v130, v134, v134
	v_mul_f32_e32 v131, v135, v135
	v_fmac_f32_e32 v122, v159, v159
	v_pk_mov_b32 v[132:133], v[160:161], v[158:159] op_sel:[1,0]
	v_add_f32_e32 v122, v131, v122
	v_mul_f32_e32 v132, v132, v132
	v_mul_f32_e32 v133, v133, v133
	v_add_f32_e32 v122, v130, v122
	v_and_b32_e32 v124, 64, v238
	v_pk_mov_b32 v[134:135], v[156:157], v[136:137] op_sel:[1,0]
	v_add_f32_e32 v122, v133, v122
	v_xor_b32_e32 v123, 16, v238
	v_add_u32_e32 v124, 64, v124
	v_mul_f32_e32 v134, v134, v134
	v_mul_f32_e32 v135, v135, v135
	v_add_f32_e32 v122, v132, v122
	v_cmp_lt_i32_e32 vcc, v123, v124
	v_add_f32_e32 v122, v135, v122
	v_add_f32_e32 v122, v134, v122
	v_cndmask_b32_e32 v123, v238, v123, vcc
	v_lshlrev_b32_e32 v123, 2, v123
	v_mov_b32_e32 v123, v122
	s_nop 1
	v_permlane16_swap_b32 v123, v122
	v_readlane_b32 s5, v253, 18
	s_waitcnt lgkmcnt(0)
	v_add_f32_e32 v122, v122, v123
	v_xor_b32_e32 v123, 32, v238
	v_cmp_lt_i32_e32 vcc, v123, v124
	s_nop 1
	v_cndmask_b32_e32 v123, v238, v123, vcc
	v_lshlrev_b32_e32 v123, 2, v123
	v_mov_b32_e32 v123, v122
	s_nop 1
	v_permlane32_swap_b32 v123, v122
	s_waitcnt lgkmcnt(0)
	v_add_f32_e32 v122, v122, v123
	v_fmamk_f32 v122, v122, 0x3c800000, v236
	v_rsq_f32_e32 v134, v122
	v_lshrrev_b32_e32 v122, 2, v180
	v_and_b32_e32 v122, 0x3f0, v122
	v_add_u32_e32 v122, v122, v177
	v_lshl_add_u32 v126, v122, 3, s5
	ds_read_b128 v[122:125], v126
	ds_read_b128 v[128:131], v126 offset:16
	v_mul_f32_e32 v126, v54, v134
	v_mul_f32_e32 v127, v55, v134
	v_mul_f32_e32 v132, v154, v134
	v_mul_f32_e32 v133, v155, v134
	v_mul_f32_e32 v126, v166, v126
	v_mul_f32_e32 v127, v167, v127
	v_mul_f32_e32 v132, v168, v132
	v_mul_f32_e32 v133, v169, v133
	s_waitcnt lgkmcnt(0)
	v_mov_b32_e32 v167, v124
	v_mov_b32_e32 v168, v122
	v_mov_b32_e32 v169, v125
	v_mov_b32_e32 v182, v124
	v_mov_b32_e32 v183, v122
	v_mov_b32_e32 v122, v125
	v_pk_mov_b32 v[124:125], v[132:133], v[126:127] op_sel:[1,0]
	v_mov_b32_e32 v166, v123
	v_mul_f32_e32 v168, v168, v126
	v_mul_f32_e32 v169, v169, v127
	v_mul_f32_e32 v122, v122, v124
	v_mul_f32_e32 v123, v123, v125
	v_mul_f32_e32 v124, v56, v134
	v_mul_f32_e32 v125, v57, v134
	v_pk_mov_b32 v[184:185], v[126:127], v[132:133] op_sel:[1,0]
	v_fma_f32 v126, v166, v132, v168
	v_fma_f32 v127, v167, v133, v169
	v_mul_f32_e32 v124, v162, v124
	v_mul_f32_e32 v125, v163, v125
	v_mov_b32_e32 v163, v130
	v_mov_b32_e32 v166, v130
	v_lshlrev_b32_e32 v130, 4, v179
	v_mul_f32_e32 v132, v152, v134
	v_mul_f32_e32 v133, v153, v134
	v_and_b32_e32 v130, 0x3f0, v130
	v_mul_f32_e32 v132, v164, v132
	v_mul_f32_e32 v133, v165, v133
	v_mov_b32_e32 v164, v128
	v_mov_b32_e32 v165, v131
	v_add_u32_e32 v130, v130, v177
	v_mov_b32_e32 v162, v129
	v_mul_f32_e32 v164, v164, v124
	v_mul_f32_e32 v165, v165, v125
	v_mov_b32_e32 v167, v128
	v_pk_mov_b32 v[168:169], v[124:125], v[132:133] op_sel:[1,0]
	v_mov_b32_e32 v128, v131
	v_pk_mov_b32 v[124:125], v[132:133], v[124:125] op_sel:[1,0]
	v_lshl_add_u32 v135, v130, 3, s5
	v_mul_f32_e32 v124, v128, v124
	v_mul_f32_e32 v125, v129, v125
	v_fma_f32 v128, v162, v132, v164
	v_fma_f32 v129, v163, v133, v165
	ds_read_b128 v[130:133], v135
	ds_read_b128 v[162:165], v135 offset:16
	v_fma_f32 v124, v166, v168, -v124
	v_fma_f32 v125, v167, v169, -v125
	v_mul_f32_e32 v166, v46, v134
	v_mul_f32_e32 v167, v47, v134
	v_fma_f32 v122, v182, v184, -v122
	v_fma_f32 v123, v183, v185, -v123
	v_mul_f32_e32 v158, v158, v166
	v_mul_f32_e32 v159, v159, v167
	v_mul_f32_e32 v166, v150, v134
	v_mul_f32_e32 v167, v151, v134
	s_waitcnt lgkmcnt(0)
	v_mov_b32_e32 v168, v130
	v_mul_f32_e32 v160, v160, v166
	v_mul_f32_e32 v161, v161, v167
	v_mov_b32_e32 v169, v133
	v_mov_b32_e32 v167, v132
	v_mul_f32_e32 v168, v168, v158
	v_mul_f32_e32 v169, v169, v159
	v_mov_b32_e32 v182, v132
	v_mov_b32_e32 v183, v130
	v_pk_mov_b32 v[184:185], v[158:159], v[160:161] op_sel:[1,0]
	v_mov_b32_e32 v130, v133
	v_pk_mov_b32 v[132:133], v[160:161], v[158:159] op_sel:[1,0]
	v_mul_f32_e32 v158, v48, v134
	v_mul_f32_e32 v159, v49, v134
	v_mul_f32_e32 v135, v149, v134
	v_mul_f32_e32 v134, v148, v134
	v_mov_b32_e32 v166, v131
	v_mul_f32_e32 v130, v130, v132
	v_mul_f32_e32 v131, v131, v133
	v_mul_f32_e32 v136, v136, v158
	v_mul_f32_e32 v137, v137, v159
	v_mul_f32_e32 v156, v156, v134
	v_mul_f32_e32 v157, v157, v135
	v_mov_b32_e32 v134, v162
	v_mov_b32_e32 v135, v165
	v_fma_f32 v132, v182, v184, -v130
	v_fma_f32 v133, v183, v185, -v131
	v_fma_f32 v130, v166, v160, v168
	v_fma_f32 v131, v167, v161, v169
	v_mul_f32_e32 v160, v134, v136
	v_mul_f32_e32 v161, v135, v137
	v_mov_b32_e32 v135, v162
	v_pk_mov_b32 v[166:167], v[136:137], v[156:157] op_sel:[1,0]
	v_mov_b32_e32 v162, v165
	v_pk_mov_b32 v[136:137], v[156:157], v[136:137] op_sel:[1,0]
	v_mov_b32_e32 v158, v163
	v_mov_b32_e32 v159, v164
	v_mov_b32_e32 v134, v164
	v_mul_f32_e32 v136, v162, v136
	v_mul_f32_e32 v137, v163, v137
	s_nop 0
	v_fma_f32 v134, v134, v166, -v136
	v_fma_f32 v135, v135, v167, -v137
	v_fma_f32 v136, v158, v156, v160
	v_fma_f32 v137, v159, v157, v161
	v_cndmask_b32_e64 v156, 0, 1, s[44:45]
	v_cmp_ne_u32_e64 s[42:43], 1, v156
	s_andn2_b64 vcc, exec, s[44:45]
	s_cbranch_vccz .LBB0_776
	s_branch .LBB0_777
.LBB0_775:
	v_mul_f32_e32 v126, v130, v170
	v_mul_f32_e32 v127, v131, v170
	v_mul_f32_e32 v128, v132, v170
	v_mul_f32_e32 v129, v133, v170
	v_mul_f32_e32 v130, v122, v170
	v_mul_f32_e32 v131, v123, v170
	v_mul_f32_e32 v136, v124, v170
	v_mul_f32_e32 v137, v125, v170
	v_pk_mov_b32 v[132:133], v[158:159], v[160:161] op_sel:[1,0]
	v_pk_mov_b32 v[124:125], v[162:163], v[164:165] op_sel:[1,0]
	v_pk_mov_b32 v[122:123], v[166:167], v[168:169] op_sel:[1,0]
	v_cndmask_b32_e64 v156, 0, 1, s[44:45]
	v_cmp_ne_u32_e64 s[42:43], 1, v156
	s_andn2_b64 vcc, exec, s[44:45]
	s_cbranch_vccnz .LBB0_777
.LBB0_776:
	v_mul_f32_e32 v122, s68, v122
	v_mul_f32_e32 v123, s68, v123
	v_mul_f32_e32 v124, s68, v124
	v_mul_f32_e32 v125, s68, v125
	v_mul_f32_e32 v126, s68, v126
	v_mul_f32_e32 v127, s68, v127
	v_mul_f32_e32 v128, s68, v128
	v_mul_f32_e32 v129, s68, v129
	v_mul_f32_e32 v132, s68, v132
	v_mul_f32_e32 v133, s68, v133
	v_mul_f32_e32 v134, s68, v134
	v_mul_f32_e32 v135, s68, v135
	v_mul_f32_e32 v130, s68, v130
	v_mul_f32_e32 v131, s68, v131
	v_mul_f32_e32 v136, s68, v136
	v_mul_f32_e32 v137, s68, v137

.LBB0_781:
	v_mov_b32_e32 v137, v175
	s_nop 0
	v_mov_b32_e32 v123, v119
	v_lshl_add_u32 v122, v137, 2, s97
	ds_read_b32 v136, v122 offset:64
	v_mov_b32_e32 v119, v115
	v_mov_b32_e32 v122, v114
	v_add3_u32 v158, v137, s94, 16
	v_add_u32_e32 v157, s66, v158
	s_waitcnt lgkmcnt(0)
	v_mul_f32_e32 v134, v118, v136
	v_mul_f32_e32 v135, v119, v136
	v_mov_b32_e32 v118, v116
	v_mov_b32_e32 v119, v121
	v_mul_f32_e32 v128, v118, v136
	v_mul_f32_e32 v129, v119, v136
	v_mov_b32_e32 v119, v111
	v_mov_b32_e32 v111, v107
	v_mov_b32_e32 v121, v117
	v_mul_f32_e32 v126, v110, v136
	v_mul_f32_e32 v127, v111, v136
	v_mov_b32_e32 v110, v108
	v_mov_b32_e32 v111, v113
	v_mov_b32_e32 v113, v109
	v_mul_f32_e32 v132, v122, v136
	v_mul_f32_e32 v133, v123, v136
	v_mul_f32_e32 v130, v120, v136
	v_mul_f32_e32 v131, v121, v136
	v_mov_b32_e32 v118, v106
	v_mul_f32_e32 v120, v110, v136
	v_mul_f32_e32 v121, v111, v136
	v_mul_f32_e32 v122, v112, v136
	v_mul_f32_e32 v123, v113, v136
	v_mul_f32_e32 v124, v118, v136
	v_mul_f32_e32 v125, v119, v136
	s_and_b64 vcc, exec, s[40:41]
	v_pk_mov_b32 v[118:119], v[120:121], v[122:123] op_sel:[1,0]
	s_cbranch_vccnz .LBB0_783
	v_mul_f32_e32 v106, v134, v134
	v_mul_f32_e32 v107, v135, v135
	v_mul_f32_e32 v108, v132, v132
	v_mul_f32_e32 v109, v133, v133
	v_mul_f32_e32 v110, v130, v130
	v_mul_f32_e32 v111, v131, v131
	v_add_f32_e32 v106, v106, v109
	v_mul_f32_e32 v112, v128, v128
	v_mul_f32_e32 v113, v129, v129
	v_add_f32_e32 v106, v110, v106
	v_add_f32_e32 v106, v113, v106
	v_add_f32_e32 v106, v108, v106
	v_add_f32_e32 v106, v107, v106
	v_add_f32_e32 v106, v112, v106
	v_add_f32_e32 v106, v111, v106
	v_fmac_f32_e32 v106, v126, v126
	v_mul_f32_e32 v114, v118, v118
	v_mul_f32_e32 v115, v119, v119
	v_fmac_f32_e32 v106, v125, v125
	v_pk_mov_b32 v[116:117], v[126:127], v[124:125] op_sel:[1,0]
	v_add_f32_e32 v106, v115, v106
	v_mul_f32_e32 v116, v116, v116
	v_mul_f32_e32 v117, v117, v117
	v_add_f32_e32 v106, v114, v106
	v_and_b32_e32 v108, 64, v238
	v_pk_mov_b32 v[118:119], v[122:123], v[120:121] op_sel:[1,0]
	v_add_f32_e32 v106, v117, v106
	v_xor_b32_e32 v107, 16, v238
	v_add_u32_e32 v108, 64, v108
	v_mul_f32_e32 v118, v118, v118
	v_mul_f32_e32 v119, v119, v119
	v_add_f32_e32 v106, v116, v106
	v_cmp_lt_i32_e32 vcc, v107, v108
	v_add_f32_e32 v106, v119, v106
	v_add_f32_e32 v106, v118, v106
	v_cndmask_b32_e32 v107, v238, v107, vcc
	v_lshlrev_b32_e32 v107, 2, v107
	v_mov_b32_e32 v107, v106
	s_nop 1
	v_permlane16_swap_b32 v107, v106
	v_readlane_b32 s5, v253, 18
	s_waitcnt lgkmcnt(0)
	v_add_f32_e32 v106, v106, v107
	v_xor_b32_e32 v107, 32, v238
	v_cmp_lt_i32_e32 vcc, v107, v108
	s_nop 1
	v_cndmask_b32_e32 v107, v238, v107, vcc
	v_lshlrev_b32_e32 v107, 2, v107
	v_mov_b32_e32 v107, v106
	s_nop 1
	v_permlane32_swap_b32 v107, v106
	s_waitcnt lgkmcnt(0)
	v_add_f32_e32 v106, v106, v107
	v_fmamk_f32 v106, v106, 0x3c800000, v236
	v_rsq_f32_e32 v118, v106
	v_lshrrev_b32_e32 v106, 2, v157
	v_and_b32_e32 v106, 0x3f0, v106
	v_add_u32_e32 v106, v106, v177
	v_lshl_add_u32 v110, v106, 3, s5
	ds_read_b128 v[106:109], v110
	ds_read_b128 v[112:115], v110 offset:16
	v_mul_f32_e32 v110, v54, v118
	v_mul_f32_e32 v111, v55, v118
	v_mul_f32_e32 v116, v154, v118
	v_mul_f32_e32 v117, v155, v118
	v_mul_f32_e32 v110, v132, v110
	v_mul_f32_e32 v111, v133, v111
	v_mul_f32_e32 v116, v134, v116
	v_mul_f32_e32 v117, v135, v117
	s_waitcnt lgkmcnt(0)
	v_mov_b32_e32 v133, v108
	v_mov_b32_e32 v134, v106
	v_mov_b32_e32 v135, v109
	v_mov_b32_e32 v160, v108
	v_mov_b32_e32 v161, v106
	v_mov_b32_e32 v106, v109
	v_pk_mov_b32 v[108:109], v[116:117], v[110:111] op_sel:[1,0]
	v_mov_b32_e32 v132, v107
	v_mul_f32_e32 v134, v134, v110
	v_mul_f32_e32 v135, v135, v111
	v_mul_f32_e32 v106, v106, v108
	v_mul_f32_e32 v107, v107, v109
	v_mul_f32_e32 v108, v56, v118
	v_mul_f32_e32 v109, v57, v118
	v_pk_mov_b32 v[162:163], v[110:111], v[116:117] op_sel:[1,0]
	v_fma_f32 v110, v132, v116, v134
	v_fma_f32 v111, v133, v117, v135
	v_mul_f32_e32 v108, v128, v108
	v_mul_f32_e32 v109, v129, v109
	v_mov_b32_e32 v129, v114
	v_mov_b32_e32 v132, v114
	v_lshlrev_b32_e32 v114, 4, v158
	v_mul_f32_e32 v116, v152, v118
	v_mul_f32_e32 v117, v153, v118
	v_and_b32_e32 v114, 0x3f0, v114
	v_mul_f32_e32 v116, v130, v116
	v_mul_f32_e32 v117, v131, v117
	v_mov_b32_e32 v130, v112
	v_mov_b32_e32 v131, v115
	v_add_u32_e32 v114, v114, v177
	v_mov_b32_e32 v128, v113
	v_mul_f32_e32 v130, v130, v108
	v_mul_f32_e32 v131, v131, v109
	v_mov_b32_e32 v133, v112
	v_pk_mov_b32 v[134:135], v[108:109], v[116:117] op_sel:[1,0]
	v_mov_b32_e32 v112, v115
	v_pk_mov_b32 v[108:109], v[116:117], v[108:109] op_sel:[1,0]
	v_lshl_add_u32 v119, v114, 3, s5
	v_mul_f32_e32 v108, v112, v108
	v_mul_f32_e32 v109, v113, v109
	v_fma_f32 v112, v128, v116, v130
	v_fma_f32 v113, v129, v117, v131
	ds_read_b128 v[114:117], v119
	ds_read_b128 v[128:131], v119 offset:16
	v_fma_f32 v108, v132, v134, -v108
	v_fma_f32 v109, v133, v135, -v109
	v_mul_f32_e32 v132, v46, v118
	v_mul_f32_e32 v133, v47, v118
	v_fma_f32 v106, v160, v162, -v106
	v_fma_f32 v107, v161, v163, -v107
	v_mul_f32_e32 v124, v124, v132
	v_mul_f32_e32 v125, v125, v133
	v_mul_f32_e32 v132, v150, v118
	v_mul_f32_e32 v133, v151, v118
	s_waitcnt lgkmcnt(0)
	v_mov_b32_e32 v134, v114
	v_mul_f32_e32 v126, v126, v132
	v_mul_f32_e32 v127, v127, v133
	v_mov_b32_e32 v135, v117
	v_mov_b32_e32 v133, v116
	v_mul_f32_e32 v134, v134, v124
	v_mul_f32_e32 v135, v135, v125
	v_mov_b32_e32 v158, v116
	v_mov_b32_e32 v159, v114
	v_pk_mov_b32 v[160:161], v[124:125], v[126:127] op_sel:[1,0]
	v_mov_b32_e32 v114, v117
	v_pk_mov_b32 v[116:117], v[126:127], v[124:125] op_sel:[1,0]
	v_mul_f32_e32 v124, v48, v118
	v_mul_f32_e32 v125, v49, v118
	v_mul_f32_e32 v119, v149, v118
	v_mul_f32_e32 v118, v148, v118
	v_mov_b32_e32 v132, v115
	v_mul_f32_e32 v114, v114, v116
	v_mul_f32_e32 v115, v115, v117
	v_mul_f32_e32 v120, v120, v124
	v_mul_f32_e32 v121, v121, v125
	v_mul_f32_e32 v122, v122, v118
	v_mul_f32_e32 v123, v123, v119
	v_mov_b32_e32 v118, v128
	v_mov_b32_e32 v119, v131
	v_fma_f32 v116, v158, v160, -v114
	v_fma_f32 v117, v159, v161, -v115
	v_fma_f32 v114, v132, v126, v134
	v_fma_f32 v115, v133, v127, v135
	v_mul_f32_e32 v126, v118, v120
	v_mul_f32_e32 v127, v119, v121
	v_mov_b32_e32 v119, v128
	v_pk_mov_b32 v[132:133], v[120:121], v[122:123] op_sel:[1,0]
	v_mov_b32_e32 v128, v131
	v_pk_mov_b32 v[120:121], v[122:123], v[120:121] op_sel:[1,0]
	v_mov_b32_e32 v124, v129
	v_mov_b32_e32 v125, v130
	v_mov_b32_e32 v118, v130
	v_mul_f32_e32 v120, v128, v120
	v_mul_f32_e32 v121, v129, v121
	s_nop 0
	v_fma_f32 v118, v118, v132, -v120
	v_fma_f32 v119, v119, v133, -v121
	v_fma_f32 v120, v124, v122, v126
	v_fma_f32 v121, v125, v123, v127
	s_and_b64 vcc, exec, s[42:43]
	s_cbranch_vccz .LBB0_784
	s_branch .LBB0_785
.LBB0_783:
	v_mul_f32_e32 v110, v114, v136
	v_mul_f32_e32 v111, v115, v136
	v_mul_f32_e32 v112, v116, v136
	v_mul_f32_e32 v113, v117, v136
	v_mul_f32_e32 v114, v106, v136
	v_mul_f32_e32 v115, v107, v136
	v_mul_f32_e32 v120, v108, v136
	v_mul_f32_e32 v121, v109, v136
	v_pk_mov_b32 v[116:117], v[124:125], v[126:127] op_sel:[1,0]
	v_pk_mov_b32 v[108:109], v[128:129], v[130:131] op_sel:[1,0]
	v_pk_mov_b32 v[106:107], v[132:133], v[134:135] op_sel:[1,0]
	s_and_b64 vcc, exec, s[42:43]
	s_cbranch_vccnz .LBB0_785
.LBB0_784:
	v_mul_f32_e32 v106, s68, v106
	v_mul_f32_e32 v107, s68, v107
	v_mul_f32_e32 v108, s68, v108
	v_mul_f32_e32 v109, s68, v109
	v_mul_f32_e32 v110, s68, v110
	v_mul_f32_e32 v111, s68, v111
	v_mul_f32_e32 v112, s68, v112
	v_mul_f32_e32 v113, s68, v113
	v_mul_f32_e32 v116, s68, v116
	v_mul_f32_e32 v117, s68, v117
	v_mul_f32_e32 v118, s68, v118
	v_mul_f32_e32 v119, s68, v119
	v_mul_f32_e32 v114, s68, v114
	v_mul_f32_e32 v115, s68, v115
	v_mul_f32_e32 v120, s68, v120
	v_mul_f32_e32 v121, s68, v121

.LBB0_789:
	v_mov_b32_e32 v121, v175
	s_nop 0
	v_mov_b32_e32 v107, v103
	v_lshl_add_u32 v106, v121, 2, s97
	ds_read_b32 v120, v106 offset:128
	v_mov_b32_e32 v103, v99
	v_mov_b32_e32 v106, v98
	v_add3_u32 v123, v121, s94, 32
	v_add_u32_e32 v122, s66, v123
	s_waitcnt lgkmcnt(0)
	v_mul_f32_e32 v118, v102, v120
	v_mul_f32_e32 v119, v103, v120
	v_mov_b32_e32 v102, v100
	v_mov_b32_e32 v103, v105
	v_mul_f32_e32 v112, v102, v120
	v_mul_f32_e32 v113, v103, v120
	v_mov_b32_e32 v103, v95
	v_mov_b32_e32 v95, v91
	v_mov_b32_e32 v105, v101
	v_mul_f32_e32 v110, v94, v120
	v_mul_f32_e32 v111, v95, v120
	v_mov_b32_e32 v94, v92
	v_mov_b32_e32 v95, v97
	v_mov_b32_e32 v97, v93
	v_mul_f32_e32 v116, v106, v120
	v_mul_f32_e32 v117, v107, v120
	v_mul_f32_e32 v114, v104, v120
	v_mul_f32_e32 v115, v105, v120
	v_mov_b32_e32 v102, v90
	v_mul_f32_e32 v104, v94, v120
	v_mul_f32_e32 v105, v95, v120
	v_mul_f32_e32 v106, v96, v120
	v_mul_f32_e32 v107, v97, v120
	v_mul_f32_e32 v108, v102, v120
	v_mul_f32_e32 v109, v103, v120
	s_and_b64 vcc, exec, s[40:41]
	v_pk_mov_b32 v[102:103], v[104:105], v[106:107] op_sel:[1,0]
	s_cbranch_vccnz .LBB0_791
	v_mul_f32_e32 v90, v118, v118
	v_mul_f32_e32 v91, v119, v119
	v_mul_f32_e32 v92, v116, v116
	v_mul_f32_e32 v93, v117, v117
	v_mul_f32_e32 v94, v114, v114
	v_mul_f32_e32 v95, v115, v115
	v_add_f32_e32 v90, v90, v93
	v_mul_f32_e32 v96, v112, v112
	v_mul_f32_e32 v97, v113, v113
	v_add_f32_e32 v90, v94, v90
	v_add_f32_e32 v90, v97, v90
	v_add_f32_e32 v90, v92, v90
	v_add_f32_e32 v90, v91, v90
	v_add_f32_e32 v90, v96, v90
	v_add_f32_e32 v90, v95, v90
	v_fmac_f32_e32 v90, v110, v110
	v_mul_f32_e32 v98, v102, v102
	v_mul_f32_e32 v99, v103, v103
	v_fmac_f32_e32 v90, v109, v109
	v_pk_mov_b32 v[100:101], v[110:111], v[108:109] op_sel:[1,0]
	v_add_f32_e32 v90, v99, v90
	v_mul_f32_e32 v100, v100, v100
	v_mul_f32_e32 v101, v101, v101
	v_add_f32_e32 v90, v98, v90
	v_and_b32_e32 v92, 64, v238
	v_pk_mov_b32 v[102:103], v[106:107], v[104:105] op_sel:[1,0]
	v_add_f32_e32 v90, v101, v90
	v_xor_b32_e32 v91, 16, v238
	v_add_u32_e32 v92, 64, v92
	v_mul_f32_e32 v102, v102, v102
	v_mul_f32_e32 v103, v103, v103
	v_add_f32_e32 v90, v100, v90
	v_cmp_lt_i32_e32 vcc, v91, v92
	v_add_f32_e32 v90, v103, v90
	v_add_f32_e32 v90, v102, v90
	v_cndmask_b32_e32 v91, v238, v91, vcc
	v_lshlrev_b32_e32 v91, 2, v91
	v_mov_b32_e32 v91, v90
	s_nop 1
	v_permlane16_swap_b32 v91, v90
	v_readlane_b32 s5, v253, 18
	s_waitcnt lgkmcnt(0)
	v_add_f32_e32 v90, v90, v91
	v_xor_b32_e32 v91, 32, v238
	v_cmp_lt_i32_e32 vcc, v91, v92
	s_nop 1
	v_cndmask_b32_e32 v91, v238, v91, vcc
	v_lshlrev_b32_e32 v91, 2, v91
	v_mov_b32_e32 v91, v90
	s_nop 1
	v_permlane32_swap_b32 v91, v90
	s_waitcnt lgkmcnt(0)
	v_add_f32_e32 v90, v90, v91
	v_fmamk_f32 v90, v90, 0x3c800000, v236
	v_rsq_f32_e32 v102, v90
	v_lshrrev_b32_e32 v90, 2, v122
	v_and_b32_e32 v90, 0x3f0, v90
	v_add_u32_e32 v90, v90, v177
	v_lshl_add_u32 v94, v90, 3, s5
	ds_read_b128 v[90:93], v94
	ds_read_b128 v[96:99], v94 offset:16
	v_mul_f32_e32 v94, v54, v102
	v_mul_f32_e32 v95, v55, v102
	v_mul_f32_e32 v100, v154, v102
	v_mul_f32_e32 v101, v155, v102
	v_mul_f32_e32 v94, v116, v94
	v_mul_f32_e32 v95, v117, v95
	v_mul_f32_e32 v100, v118, v100
	v_mul_f32_e32 v101, v119, v101
	s_waitcnt lgkmcnt(0)
	v_mov_b32_e32 v117, v92
	v_mov_b32_e32 v118, v90
	v_mov_b32_e32 v119, v93
	v_mov_b32_e32 v124, v92
	v_mov_b32_e32 v125, v90
	v_mov_b32_e32 v90, v93
	v_pk_mov_b32 v[92:93], v[100:101], v[94:95] op_sel:[1,0]
	v_mov_b32_e32 v116, v91
	v_mul_f32_e32 v118, v118, v94
	v_mul_f32_e32 v119, v119, v95
	v_mul_f32_e32 v90, v90, v92
	v_mul_f32_e32 v91, v91, v93
	v_mul_f32_e32 v92, v56, v102
	v_mul_f32_e32 v93, v57, v102
	v_pk_mov_b32 v[126:127], v[94:95], v[100:101] op_sel:[1,0]
	v_fma_f32 v94, v116, v100, v118
	v_fma_f32 v95, v117, v101, v119
	v_mul_f32_e32 v92, v112, v92
	v_mul_f32_e32 v93, v113, v93
	v_mov_b32_e32 v113, v98
	v_mov_b32_e32 v116, v98
	v_lshlrev_b32_e32 v98, 4, v123
	v_mul_f32_e32 v100, v152, v102
	v_mul_f32_e32 v101, v153, v102
	v_and_b32_e32 v98, 0x3f0, v98
	v_mul_f32_e32 v100, v114, v100
	v_mul_f32_e32 v101, v115, v101
	v_mov_b32_e32 v114, v96
	v_mov_b32_e32 v115, v99
	v_add_u32_e32 v98, v98, v177
	v_mov_b32_e32 v112, v97
	v_mul_f32_e32 v114, v114, v92
	v_mul_f32_e32 v115, v115, v93
	v_mov_b32_e32 v117, v96
	v_pk_mov_b32 v[118:119], v[92:93], v[100:101] op_sel:[1,0]
	v_mov_b32_e32 v96, v99
	v_pk_mov_b32 v[92:93], v[100:101], v[92:93] op_sel:[1,0]
	v_lshl_add_u32 v103, v98, 3, s5
	v_mul_f32_e32 v92, v96, v92
	v_mul_f32_e32 v93, v97, v93
	v_fma_f32 v96, v112, v100, v114
	v_fma_f32 v97, v113, v101, v115
	ds_read_b128 v[98:101], v103
	ds_read_b128 v[112:115], v103 offset:16
	v_fma_f32 v92, v116, v118, -v92
	v_fma_f32 v93, v117, v119, -v93
	v_mul_f32_e32 v116, v46, v102
	v_mul_f32_e32 v117, v47, v102
	v_fma_f32 v90, v124, v126, -v90
	v_fma_f32 v91, v125, v127, -v91
	v_mul_f32_e32 v108, v108, v116
	v_mul_f32_e32 v109, v109, v117
	v_mul_f32_e32 v116, v150, v102
	v_mul_f32_e32 v117, v151, v102
	s_waitcnt lgkmcnt(0)
	v_mov_b32_e32 v118, v98
	v_mul_f32_e32 v110, v110, v116
	v_mul_f32_e32 v111, v111, v117
	v_mov_b32_e32 v119, v101
	v_mov_b32_e32 v117, v100
	v_mul_f32_e32 v118, v118, v108
	v_mul_f32_e32 v119, v119, v109
	v_mov_b32_e32 v124, v100
	v_mov_b32_e32 v125, v98
	v_pk_mov_b32 v[126:127], v[108:109], v[110:111] op_sel:[1,0]
	v_mov_b32_e32 v98, v101
	v_pk_mov_b32 v[100:101], v[110:111], v[108:109] op_sel:[1,0]
	v_mul_f32_e32 v108, v48, v102
	v_mul_f32_e32 v109, v49, v102
	v_mul_f32_e32 v103, v149, v102
	v_mul_f32_e32 v102, v148, v102
	v_mov_b32_e32 v116, v99
	v_mul_f32_e32 v98, v98, v100
	v_mul_f32_e32 v99, v99, v101
	v_mul_f32_e32 v104, v104, v108
	v_mul_f32_e32 v105, v105, v109
	v_mul_f32_e32 v106, v106, v102
	v_mul_f32_e32 v107, v107, v103
	v_mov_b32_e32 v102, v112
	v_mov_b32_e32 v103, v115
	v_fma_f32 v100, v124, v126, -v98
	v_fma_f32 v101, v125, v127, -v99
	v_fma_f32 v98, v116, v110, v118
	v_fma_f32 v99, v117, v111, v119
	v_mul_f32_e32 v110, v102, v104
	v_mul_f32_e32 v111, v103, v105
	v_mov_b32_e32 v103, v112
	v_pk_mov_b32 v[116:117], v[104:105], v[106:107] op_sel:[1,0]
	v_mov_b32_e32 v112, v115
	v_pk_mov_b32 v[104:105], v[106:107], v[104:105] op_sel:[1,0]
	v_mov_b32_e32 v108, v113
	v_mov_b32_e32 v109, v114
	v_mov_b32_e32 v102, v114
	v_mul_f32_e32 v104, v112, v104
	v_mul_f32_e32 v105, v113, v105
	s_nop 0
	v_fma_f32 v102, v102, v116, -v104
	v_fma_f32 v103, v103, v117, -v105
	v_fma_f32 v104, v108, v106, v110
	v_fma_f32 v105, v109, v107, v111
	s_and_b64 vcc, exec, s[42:43]
	s_cbranch_vccz .LBB0_792
	s_branch .LBB0_793
.LBB0_791:
	v_mul_f32_e32 v94, v98, v120
	v_mul_f32_e32 v95, v99, v120
	v_mul_f32_e32 v96, v100, v120
	v_mul_f32_e32 v97, v101, v120
	v_mul_f32_e32 v98, v90, v120
	v_mul_f32_e32 v99, v91, v120
	v_mul_f32_e32 v104, v92, v120
	v_mul_f32_e32 v105, v93, v120
	v_pk_mov_b32 v[100:101], v[108:109], v[110:111] op_sel:[1,0]
	v_pk_mov_b32 v[92:93], v[112:113], v[114:115] op_sel:[1,0]
	v_pk_mov_b32 v[90:91], v[116:117], v[118:119] op_sel:[1,0]
	s_and_b64 vcc, exec, s[42:43]
	s_cbranch_vccnz .LBB0_793
.LBB0_792:
	v_mul_f32_e32 v90, s68, v90
	v_mul_f32_e32 v91, s68, v91
	v_mul_f32_e32 v92, s68, v92
	v_mul_f32_e32 v93, s68, v93
	v_mul_f32_e32 v94, s68, v94
	v_mul_f32_e32 v95, s68, v95
	v_mul_f32_e32 v96, s68, v96
	v_mul_f32_e32 v97, s68, v97
	v_mul_f32_e32 v100, s68, v100
	v_mul_f32_e32 v101, s68, v101
	v_mul_f32_e32 v102, s68, v102
	v_mul_f32_e32 v103, s68, v103
	v_mul_f32_e32 v98, s68, v98
	v_mul_f32_e32 v99, s68, v99
	v_mul_f32_e32 v104, s68, v104
	v_mul_f32_e32 v105, s68, v105

.LBB0_797:
	v_mov_b32_e32 v105, v175
	s_nop 0
	v_mov_b32_e32 v91, v87
	v_lshl_add_u32 v90, v105, 2, s97
	ds_read_b32 v104, v90 offset:192
	v_mov_b32_e32 v87, v83
	v_mov_b32_e32 v90, v82
	v_add3_u32 v107, v105, s94, 48
	v_add_u32_e32 v106, s66, v107
	s_waitcnt lgkmcnt(0)
	v_mul_f32_e32 v102, v86, v104
	v_mul_f32_e32 v103, v87, v104
	v_mov_b32_e32 v86, v84
	v_mov_b32_e32 v87, v89
	v_mul_f32_e32 v96, v86, v104
	v_mul_f32_e32 v97, v87, v104
	v_mov_b32_e32 v87, v79
	v_mov_b32_e32 v79, v75
	v_mov_b32_e32 v89, v85
	v_mul_f32_e32 v94, v78, v104
	v_mul_f32_e32 v95, v79, v104
	v_mov_b32_e32 v78, v76
	v_mov_b32_e32 v79, v81
	v_mov_b32_e32 v81, v77
	v_mul_f32_e32 v100, v90, v104
	v_mul_f32_e32 v101, v91, v104
	v_mul_f32_e32 v98, v88, v104
	v_mul_f32_e32 v99, v89, v104
	v_mov_b32_e32 v86, v74
	v_mul_f32_e32 v88, v78, v104
	v_mul_f32_e32 v89, v79, v104
	v_mul_f32_e32 v90, v80, v104
	v_mul_f32_e32 v91, v81, v104
	v_mul_f32_e32 v92, v86, v104
	v_mul_f32_e32 v93, v87, v104
	s_and_b64 vcc, exec, s[40:41]
	v_pk_mov_b32 v[86:87], v[88:89], v[90:91] op_sel:[1,0]
	s_cbranch_vccnz .LBB0_799
	v_mul_f32_e32 v74, v102, v102
	v_mul_f32_e32 v75, v103, v103
	v_mul_f32_e32 v76, v100, v100
	v_mul_f32_e32 v77, v101, v101
	v_mul_f32_e32 v78, v98, v98
	v_mul_f32_e32 v79, v99, v99
	v_add_f32_e32 v74, v74, v77
	v_mul_f32_e32 v80, v96, v96
	v_mul_f32_e32 v81, v97, v97
	v_add_f32_e32 v74, v78, v74
	v_add_f32_e32 v74, v81, v74
	v_add_f32_e32 v74, v76, v74
	v_add_f32_e32 v74, v75, v74
	v_add_f32_e32 v74, v80, v74
	v_add_f32_e32 v74, v79, v74
	v_fmac_f32_e32 v74, v94, v94
	v_mul_f32_e32 v82, v86, v86
	v_mul_f32_e32 v83, v87, v87
	v_fmac_f32_e32 v74, v93, v93
	v_pk_mov_b32 v[84:85], v[94:95], v[92:93] op_sel:[1,0]
	v_add_f32_e32 v74, v83, v74
	v_mul_f32_e32 v84, v84, v84
	v_mul_f32_e32 v85, v85, v85
	v_add_f32_e32 v74, v82, v74
	v_and_b32_e32 v76, 64, v238
	v_pk_mov_b32 v[86:87], v[90:91], v[88:89] op_sel:[1,0]
	v_add_f32_e32 v74, v85, v74
	v_xor_b32_e32 v75, 16, v238
	v_add_u32_e32 v76, 64, v76
	v_mul_f32_e32 v86, v86, v86
	v_mul_f32_e32 v87, v87, v87
	v_add_f32_e32 v74, v84, v74
	v_cmp_lt_i32_e32 vcc, v75, v76
	v_add_f32_e32 v74, v87, v74
	v_add_f32_e32 v74, v86, v74
	v_cndmask_b32_e32 v75, v238, v75, vcc
	v_lshlrev_b32_e32 v75, 2, v75
	v_mov_b32_e32 v75, v74
	s_nop 1
	v_permlane16_swap_b32 v75, v74
	v_readlane_b32 s5, v253, 18
	s_waitcnt lgkmcnt(0)
	v_add_f32_e32 v74, v74, v75
	v_xor_b32_e32 v75, 32, v238
	v_cmp_lt_i32_e32 vcc, v75, v76
	s_nop 1
	v_cndmask_b32_e32 v75, v238, v75, vcc
	v_lshlrev_b32_e32 v75, 2, v75
	v_mov_b32_e32 v75, v74
	s_nop 1
	v_permlane32_swap_b32 v75, v74
	s_waitcnt lgkmcnt(0)
	v_add_f32_e32 v74, v74, v75
	v_fmamk_f32 v74, v74, 0x3c800000, v236
	v_rsq_f32_e32 v86, v74
	v_lshrrev_b32_e32 v74, 2, v106
	v_and_b32_e32 v74, 0x3f0, v74
	v_add_u32_e32 v74, v74, v177
	v_lshl_add_u32 v78, v74, 3, s5
	ds_read_b128 v[74:77], v78
	ds_read_b128 v[80:83], v78 offset:16
	v_mul_f32_e32 v78, v54, v86
	v_mul_f32_e32 v79, v55, v86
	v_mul_f32_e32 v84, v154, v86
	v_mul_f32_e32 v85, v155, v86
	v_mul_f32_e32 v78, v100, v78
	v_mul_f32_e32 v79, v101, v79
	v_mul_f32_e32 v84, v102, v84
	v_mul_f32_e32 v85, v103, v85
	s_waitcnt lgkmcnt(0)
	v_mov_b32_e32 v101, v76
	v_mov_b32_e32 v102, v74
	v_mov_b32_e32 v103, v77
	v_mov_b32_e32 v108, v76
	v_mov_b32_e32 v109, v74
	v_mov_b32_e32 v74, v77
	v_pk_mov_b32 v[76:77], v[84:85], v[78:79] op_sel:[1,0]
	v_mov_b32_e32 v100, v75
	v_mul_f32_e32 v102, v102, v78
	v_mul_f32_e32 v103, v103, v79
	v_mul_f32_e32 v74, v74, v76
	v_mul_f32_e32 v75, v75, v77
	v_mul_f32_e32 v76, v56, v86
	v_mul_f32_e32 v77, v57, v86
	v_pk_mov_b32 v[110:111], v[78:79], v[84:85] op_sel:[1,0]
	v_fma_f32 v78, v100, v84, v102
	v_fma_f32 v79, v101, v85, v103
	v_mul_f32_e32 v76, v96, v76
	v_mul_f32_e32 v77, v97, v77
	v_mov_b32_e32 v97, v82
	v_mov_b32_e32 v100, v82
	v_lshlrev_b32_e32 v82, 4, v107
	v_mul_f32_e32 v84, v152, v86
	v_mul_f32_e32 v85, v153, v86
	v_and_b32_e32 v82, 0x3f0, v82
	v_mul_f32_e32 v84, v98, v84
	v_mul_f32_e32 v85, v99, v85
	v_mov_b32_e32 v98, v80
	v_mov_b32_e32 v99, v83
	v_add_u32_e32 v82, v82, v177
	v_mov_b32_e32 v96, v81
	v_mul_f32_e32 v98, v98, v76
	v_mul_f32_e32 v99, v99, v77
	v_mov_b32_e32 v101, v80
	v_pk_mov_b32 v[102:103], v[76:77], v[84:85] op_sel:[1,0]
	v_mov_b32_e32 v80, v83
	v_pk_mov_b32 v[76:77], v[84:85], v[76:77] op_sel:[1,0]
	v_lshl_add_u32 v87, v82, 3, s5
	v_mul_f32_e32 v76, v80, v76
	v_mul_f32_e32 v77, v81, v77
	v_fma_f32 v80, v96, v84, v98
	v_fma_f32 v81, v97, v85, v99
	ds_read_b128 v[82:85], v87
	ds_read_b128 v[96:99], v87 offset:16
	v_fma_f32 v76, v100, v102, -v76
	v_fma_f32 v77, v101, v103, -v77
	v_mul_f32_e32 v100, v46, v86
	v_mul_f32_e32 v101, v47, v86
	v_fma_f32 v74, v108, v110, -v74
	v_fma_f32 v75, v109, v111, -v75
	v_mul_f32_e32 v92, v92, v100
	v_mul_f32_e32 v93, v93, v101
	v_mul_f32_e32 v100, v150, v86
	v_mul_f32_e32 v101, v151, v86
	s_waitcnt lgkmcnt(0)
	v_mov_b32_e32 v102, v82
	v_mul_f32_e32 v94, v94, v100
	v_mul_f32_e32 v95, v95, v101
	v_mov_b32_e32 v103, v85
	v_mov_b32_e32 v101, v84
	v_mul_f32_e32 v102, v102, v92
	v_mul_f32_e32 v103, v103, v93
	v_mov_b32_e32 v108, v84
	v_mov_b32_e32 v109, v82
	v_pk_mov_b32 v[110:111], v[92:93], v[94:95] op_sel:[1,0]
	v_mov_b32_e32 v82, v85
	v_pk_mov_b32 v[84:85], v[94:95], v[92:93] op_sel:[1,0]
	v_mul_f32_e32 v92, v48, v86
	v_mul_f32_e32 v93, v49, v86
	v_mul_f32_e32 v87, v149, v86
	v_mul_f32_e32 v86, v148, v86
	v_mov_b32_e32 v100, v83
	v_mul_f32_e32 v82, v82, v84
	v_mul_f32_e32 v83, v83, v85
	v_mul_f32_e32 v88, v88, v92
	v_mul_f32_e32 v89, v89, v93
	v_mul_f32_e32 v90, v90, v86
	v_mul_f32_e32 v91, v91, v87
	v_mov_b32_e32 v86, v96
	v_mov_b32_e32 v87, v99
	v_fma_f32 v84, v108, v110, -v82
	v_fma_f32 v85, v109, v111, -v83
	v_fma_f32 v82, v100, v94, v102
	v_fma_f32 v83, v101, v95, v103
	v_mul_f32_e32 v94, v86, v88
	v_mul_f32_e32 v95, v87, v89
	v_mov_b32_e32 v87, v96
	v_pk_mov_b32 v[100:101], v[88:89], v[90:91] op_sel:[1,0]
	v_mov_b32_e32 v96, v99
	v_pk_mov_b32 v[88:89], v[90:91], v[88:89] op_sel:[1,0]
	v_mov_b32_e32 v92, v97
	v_mov_b32_e32 v93, v98
	v_mov_b32_e32 v86, v98
	v_mul_f32_e32 v88, v96, v88
	v_mul_f32_e32 v89, v97, v89
	s_nop 0
	v_fma_f32 v86, v86, v100, -v88
	v_fma_f32 v87, v87, v101, -v89
	v_fma_f32 v88, v92, v90, v94
	v_fma_f32 v89, v93, v91, v95
	s_and_b64 vcc, exec, s[42:43]
	s_cbranch_vccz .LBB0_800
	s_branch .LBB0_801
.LBB0_799:
	v_mul_f32_e32 v78, v82, v104
	v_mul_f32_e32 v79, v83, v104
	v_mul_f32_e32 v80, v84, v104
	v_mul_f32_e32 v81, v85, v104
	v_mul_f32_e32 v82, v74, v104
	v_mul_f32_e32 v83, v75, v104
	v_mul_f32_e32 v88, v76, v104
	v_mul_f32_e32 v89, v77, v104
	v_pk_mov_b32 v[84:85], v[92:93], v[94:95] op_sel:[1,0]
	v_pk_mov_b32 v[76:77], v[96:97], v[98:99] op_sel:[1,0]
	v_pk_mov_b32 v[74:75], v[100:101], v[102:103] op_sel:[1,0]
	s_and_b64 vcc, exec, s[42:43]
	s_cbranch_vccnz .LBB0_801
.LBB0_800:
	v_mul_f32_e32 v74, s68, v74
	v_mul_f32_e32 v75, s68, v75
	v_mul_f32_e32 v76, s68, v76
	v_mul_f32_e32 v77, s68, v77
	v_mul_f32_e32 v78, s68, v78
	v_mul_f32_e32 v79, s68, v79
	v_mul_f32_e32 v80, s68, v80
	v_mul_f32_e32 v81, s68, v81
	v_mul_f32_e32 v84, s68, v84
	v_mul_f32_e32 v85, s68, v85
	v_mul_f32_e32 v86, s68, v86
	v_mul_f32_e32 v87, s68, v87
	v_mul_f32_e32 v82, s68, v82
	v_mul_f32_e32 v83, s68, v83
	v_mul_f32_e32 v88, s68, v88
	v_mul_f32_e32 v89, s68, v89

.LBB0_805:
	v_mov_b32_e32 v89, v175
	s_nop 0
	v_mov_b32_e32 v75, v71
	v_lshl_add_u32 v74, v89, 2, s97
	ds_read_b32 v88, v74 offset:512
	v_mov_b32_e32 v71, v67
	v_mov_b32_e32 v74, v66
	s_addk_i32 s4, 0x80
	v_add_u32_e32 v90, s4, v89
	s_waitcnt lgkmcnt(0)
	v_mul_f32_e32 v86, v70, v88
	v_mul_f32_e32 v87, v71, v88
	v_mov_b32_e32 v70, v68
	v_mov_b32_e32 v71, v73
	v_mul_f32_e32 v80, v70, v88
	v_mul_f32_e32 v81, v71, v88
	v_mov_b32_e32 v71, v63
	v_mov_b32_e32 v63, v59
	v_mov_b32_e32 v73, v69
	v_mul_f32_e32 v78, v62, v88
	v_mul_f32_e32 v79, v63, v88
	v_mov_b32_e32 v62, v60
	v_mov_b32_e32 v63, v65
	v_mov_b32_e32 v65, v61
	v_mul_f32_e32 v84, v74, v88
	v_mul_f32_e32 v85, v75, v88
	v_mul_f32_e32 v82, v72, v88
	v_mul_f32_e32 v83, v73, v88
	v_mov_b32_e32 v70, v58
	v_mul_f32_e32 v72, v62, v88
	v_mul_f32_e32 v73, v63, v88
	v_mul_f32_e32 v74, v64, v88
	v_mul_f32_e32 v75, v65, v88
	v_mul_f32_e32 v76, v70, v88
	v_mul_f32_e32 v77, v71, v88
	s_and_b64 vcc, exec, s[40:41]
	v_pk_mov_b32 v[70:71], v[72:73], v[74:75] op_sel:[1,0]
	s_cbranch_vccnz .LBB0_807
	v_mul_f32_e32 v58, v86, v86
	v_mul_f32_e32 v59, v87, v87
	v_mul_f32_e32 v60, v84, v84
	v_mul_f32_e32 v61, v85, v85
	v_mul_f32_e32 v62, v82, v82
	v_mul_f32_e32 v63, v83, v83
	v_add_f32_e32 v58, v58, v61
	v_mul_f32_e32 v64, v80, v80
	v_mul_f32_e32 v65, v81, v81
	v_add_f32_e32 v58, v62, v58
	v_add_f32_e32 v58, v65, v58
	v_add_f32_e32 v58, v60, v58
	v_add_f32_e32 v58, v59, v58
	v_add_f32_e32 v58, v64, v58
	v_add_f32_e32 v58, v63, v58
	v_fmac_f32_e32 v58, v78, v78
	v_mul_f32_e32 v66, v70, v70
	v_mul_f32_e32 v67, v71, v71
	v_fmac_f32_e32 v58, v77, v77
	v_pk_mov_b32 v[68:69], v[78:79], v[76:77] op_sel:[1,0]
	v_add_f32_e32 v58, v67, v58
	v_mul_f32_e32 v68, v68, v68
	v_mul_f32_e32 v69, v69, v69
	v_add_f32_e32 v58, v66, v58
	v_and_b32_e32 v60, 64, v238
	v_pk_mov_b32 v[70:71], v[74:75], v[72:73] op_sel:[1,0]
	v_add_f32_e32 v58, v69, v58
	v_xor_b32_e32 v59, 16, v238
	v_add_u32_e32 v60, 64, v60
	v_mul_f32_e32 v70, v70, v70
	v_mul_f32_e32 v71, v71, v71
	v_add_f32_e32 v58, v68, v58
	v_cmp_lt_i32_e32 vcc, v59, v60
	v_add_f32_e32 v58, v71, v58
	v_add_f32_e32 v58, v70, v58
	v_cndmask_b32_e32 v59, v238, v59, vcc
	v_lshlrev_b32_e32 v59, 2, v59
	v_mov_b32_e32 v59, v58
	s_nop 1
	v_permlane16_swap_b32 v59, v58
	v_readlane_b32 s4, v253, 18
	s_waitcnt lgkmcnt(0)
	v_add_f32_e32 v58, v58, v59
	v_xor_b32_e32 v59, 32, v238
	v_cmp_lt_i32_e32 vcc, v59, v60
	s_nop 1
	v_cndmask_b32_e32 v59, v238, v59, vcc
	v_lshlrev_b32_e32 v59, 2, v59
	v_mov_b32_e32 v59, v58
	s_nop 1
	v_permlane32_swap_b32 v59, v58
	s_waitcnt lgkmcnt(0)
	v_add_f32_e32 v58, v58, v59
	v_fmamk_f32 v58, v58, 0x3c800000, v236
	v_rsq_f32_e32 v70, v58
	v_lshrrev_b32_e32 v58, 2, v90
	v_and_b32_e32 v58, 0x3f0, v58
	v_add_u32_e32 v58, v58, v177
	v_lshl_add_u32 v62, v58, 3, s4
	ds_read_b128 v[58:61], v62
	ds_read_b128 v[64:67], v62 offset:16
	v_mul_f32_e32 v62, v54, v70
	v_mul_f32_e32 v63, v55, v70
	v_mul_f32_e32 v68, v154, v70
	v_mul_f32_e32 v69, v155, v70
	v_mul_f32_e32 v62, v84, v62
	v_mul_f32_e32 v63, v85, v63
	v_mul_f32_e32 v68, v86, v68
	v_mul_f32_e32 v69, v87, v69
	s_waitcnt lgkmcnt(0)
	v_mov_b32_e32 v85, v60
	v_mov_b32_e32 v86, v58
	v_mov_b32_e32 v87, v61
	v_mov_b32_e32 v92, v60
	v_mov_b32_e32 v93, v58
	v_mov_b32_e32 v58, v61
	v_pk_mov_b32 v[60:61], v[68:69], v[62:63] op_sel:[1,0]
	v_mov_b32_e32 v84, v59
	v_mul_f32_e32 v86, v86, v62
	v_mul_f32_e32 v87, v87, v63
	v_mul_f32_e32 v58, v58, v60
	v_mul_f32_e32 v59, v59, v61
	v_mul_f32_e32 v60, v56, v70
	v_mul_f32_e32 v61, v57, v70
	v_pk_mov_b32 v[94:95], v[62:63], v[68:69] op_sel:[1,0]
	v_fma_f32 v62, v84, v68, v86
	v_fma_f32 v63, v85, v69, v87
	v_mul_f32_e32 v60, v80, v60
	v_mul_f32_e32 v61, v81, v61
	v_mov_b32_e32 v81, v66
	v_mov_b32_e32 v84, v66
	v_lshlrev_b32_e32 v66, 4, v89
	v_mul_f32_e32 v68, v152, v70
	v_mul_f32_e32 v69, v153, v70
	v_and_b32_e32 v66, 0x3f0, v66
	v_mul_f32_e32 v68, v82, v68
	v_mul_f32_e32 v69, v83, v69
	v_mov_b32_e32 v82, v64
	v_mov_b32_e32 v83, v67
	v_add_u32_e32 v66, v66, v177
	v_mov_b32_e32 v80, v65
	v_mul_f32_e32 v82, v82, v60
	v_mul_f32_e32 v83, v83, v61
	v_mov_b32_e32 v85, v64
	v_pk_mov_b32 v[86:87], v[60:61], v[68:69] op_sel:[1,0]
	v_mov_b32_e32 v64, v67
	v_pk_mov_b32 v[60:61], v[68:69], v[60:61] op_sel:[1,0]
	v_lshl_add_u32 v71, v66, 3, s4
	v_mul_f32_e32 v60, v64, v60
	v_mul_f32_e32 v61, v65, v61
	v_fma_f32 v64, v80, v68, v82
	v_fma_f32 v65, v81, v69, v83
	ds_read_b128 v[66:69], v71
	ds_read_b128 v[80:83], v71 offset:16
	v_fma_f32 v60, v84, v86, -v60
	v_fma_f32 v61, v85, v87, -v61
	v_mul_f32_e32 v84, v46, v70
	v_mul_f32_e32 v85, v47, v70
	v_fma_f32 v58, v92, v94, -v58
	v_fma_f32 v59, v93, v95, -v59
	v_mul_f32_e32 v76, v76, v84
	v_mul_f32_e32 v77, v77, v85
	v_mul_f32_e32 v84, v150, v70
	v_mul_f32_e32 v85, v151, v70
	s_waitcnt lgkmcnt(0)
	v_mov_b32_e32 v86, v66
	v_mul_f32_e32 v78, v78, v84
	v_mul_f32_e32 v79, v79, v85
	v_mov_b32_e32 v87, v69
	v_mov_b32_e32 v85, v68
	v_mul_f32_e32 v86, v86, v76
	v_mul_f32_e32 v87, v87, v77
	v_mov_b32_e32 v92, v68
	v_mov_b32_e32 v93, v66
	v_pk_mov_b32 v[94:95], v[76:77], v[78:79] op_sel:[1,0]
	v_mov_b32_e32 v66, v69
	v_pk_mov_b32 v[68:69], v[78:79], v[76:77] op_sel:[1,0]
	v_mul_f32_e32 v76, v48, v70
	v_mul_f32_e32 v77, v49, v70
	v_mul_f32_e32 v71, v149, v70
	v_mul_f32_e32 v70, v148, v70
	v_mov_b32_e32 v84, v67
	v_mul_f32_e32 v66, v66, v68
	v_mul_f32_e32 v67, v67, v69
	v_mul_f32_e32 v72, v72, v76
	v_mul_f32_e32 v73, v73, v77
	v_mul_f32_e32 v74, v74, v70
	v_mul_f32_e32 v75, v75, v71
	v_mov_b32_e32 v70, v80
	v_mov_b32_e32 v71, v83
	v_fma_f32 v68, v92, v94, -v66
	v_fma_f32 v69, v93, v95, -v67
	v_fma_f32 v66, v84, v78, v86
	v_fma_f32 v67, v85, v79, v87
	v_mul_f32_e32 v78, v70, v72
	v_mul_f32_e32 v79, v71, v73
	v_mov_b32_e32 v71, v80
	v_pk_mov_b32 v[84:85], v[72:73], v[74:75] op_sel:[1,0]
	v_mov_b32_e32 v80, v83
	v_pk_mov_b32 v[72:73], v[74:75], v[72:73] op_sel:[1,0]
	v_mov_b32_e32 v76, v81
	v_mov_b32_e32 v77, v82
	v_mov_b32_e32 v70, v82
	v_mul_f32_e32 v72, v80, v72
	v_mul_f32_e32 v73, v81, v73
	s_nop 0
	v_fma_f32 v70, v70, v84, -v72
	v_fma_f32 v71, v71, v85, -v73
	v_fma_f32 v72, v76, v74, v78
	v_fma_f32 v73, v77, v75, v79
	s_and_b64 vcc, exec, s[42:43]
	s_cbranch_vccz .LBB0_808
	s_branch .LBB0_809
.LBB0_807:
	v_mul_f32_e32 v62, v66, v88
	v_mul_f32_e32 v63, v67, v88
	v_mul_f32_e32 v64, v68, v88
	v_mul_f32_e32 v65, v69, v88
	v_mul_f32_e32 v66, v58, v88
	v_mul_f32_e32 v67, v59, v88
	v_mul_f32_e32 v72, v60, v88
	v_mul_f32_e32 v73, v61, v88
	v_pk_mov_b32 v[68:69], v[76:77], v[78:79] op_sel:[1,0]
	v_pk_mov_b32 v[60:61], v[80:81], v[82:83] op_sel:[1,0]
	v_pk_mov_b32 v[58:59], v[84:85], v[86:87] op_sel:[1,0]
	s_and_b64 vcc, exec, s[42:43]
	s_cbranch_vccnz .LBB0_809
.LBB0_808:
	v_mul_f32_e32 v58, s68, v58
	v_mul_f32_e32 v59, s68, v59
	v_mul_f32_e32 v60, s68, v60
	v_mul_f32_e32 v61, s68, v61
	v_mul_f32_e32 v62, s68, v62
	v_mul_f32_e32 v63, s68, v63
	v_mul_f32_e32 v64, s68, v64
	v_mul_f32_e32 v65, s68, v65
	v_mul_f32_e32 v68, s68, v68
	v_mul_f32_e32 v69, s68, v69
	v_mul_f32_e32 v70, s68, v70
	v_mul_f32_e32 v71, s68, v71
	v_mul_f32_e32 v66, s68, v66
	v_mul_f32_e32 v67, s68, v67
	v_mul_f32_e32 v72, s68, v72
	v_mul_f32_e32 v73, s68, v73

.LBB0_813:
	v_mov_b32_e32 v73, v175
	s_nop 0
	v_mov_b32_e32 v59, v51
	v_lshl_add_u32 v58, v73, 2, s97
	ds_read_b32 v72, v58 offset:576
	v_mov_b32_e32 v51, v43
	s_add_i32 s4, s94, 0x90
	v_mov_b32_e32 v58, v42
	v_add_u32_e32 v75, s4, v73
	s_waitcnt lgkmcnt(0)
	v_mul_f32_e32 v70, v50, v72
	v_mul_f32_e32 v71, v51, v72
	v_mov_b32_e32 v50, v44
	v_mov_b32_e32 v51, v53
	v_mul_f32_e32 v64, v50, v72
	v_mul_f32_e32 v65, v51, v72
	v_mov_b32_e32 v51, v39
	v_mov_b32_e32 v39, v35
	v_mov_b32_e32 v53, v45
	v_mul_f32_e32 v62, v38, v72
	v_mul_f32_e32 v63, v39, v72
	v_mov_b32_e32 v38, v36
	v_mov_b32_e32 v39, v41
	v_mov_b32_e32 v41, v37
	v_mul_f32_e32 v68, v58, v72
	v_mul_f32_e32 v69, v59, v72
	v_mul_f32_e32 v66, v52, v72
	v_mul_f32_e32 v67, v53, v72
	v_mov_b32_e32 v50, v34
	v_mul_f32_e32 v52, v38, v72
	v_mul_f32_e32 v53, v39, v72
	v_mul_f32_e32 v58, v40, v72
	v_mul_f32_e32 v59, v41, v72
	v_add_u32_e32 v74, s66, v75
	v_mul_f32_e32 v60, v50, v72
	v_mul_f32_e32 v61, v51, v72
	s_and_b64 vcc, exec, s[40:41]
	v_pk_mov_b32 v[50:51], v[52:53], v[58:59] op_sel:[1,0]
	s_cbranch_vccnz .LBB0_815
	v_mul_f32_e32 v34, v70, v70
	v_mul_f32_e32 v35, v71, v71
	v_mul_f32_e32 v36, v68, v68
	v_mul_f32_e32 v37, v69, v69
	v_mul_f32_e32 v38, v66, v66
	v_mul_f32_e32 v39, v67, v67
	v_add_f32_e32 v34, v34, v37
	v_mul_f32_e32 v40, v64, v64
	v_mul_f32_e32 v41, v65, v65
	v_add_f32_e32 v34, v38, v34
	v_add_f32_e32 v34, v41, v34
	v_add_f32_e32 v34, v36, v34
	v_add_f32_e32 v34, v35, v34
	v_add_f32_e32 v34, v40, v34
	v_add_f32_e32 v34, v39, v34
	v_fmac_f32_e32 v34, v62, v62
	v_mul_f32_e32 v42, v50, v50
	v_mul_f32_e32 v43, v51, v51
	v_fmac_f32_e32 v34, v61, v61
	v_pk_mov_b32 v[44:45], v[62:63], v[60:61] op_sel:[1,0]
	v_add_f32_e32 v34, v43, v34
	v_mul_f32_e32 v44, v44, v44
	v_mul_f32_e32 v45, v45, v45
	v_add_f32_e32 v34, v42, v34
	v_and_b32_e32 v36, 64, v238
	v_pk_mov_b32 v[50:51], v[58:59], v[52:53] op_sel:[1,0]
	v_add_f32_e32 v34, v45, v34
	v_xor_b32_e32 v35, 16, v238
	v_add_u32_e32 v36, 64, v36
	v_mul_f32_e32 v50, v50, v50
	v_mul_f32_e32 v51, v51, v51
	v_add_f32_e32 v34, v44, v34
	v_cmp_lt_i32_e32 vcc, v35, v36
	v_add_f32_e32 v34, v51, v34
	v_add_f32_e32 v34, v50, v34
	v_cndmask_b32_e32 v35, v238, v35, vcc
	v_lshlrev_b32_e32 v35, 2, v35
	v_mov_b32_e32 v35, v34
	s_nop 1
	v_permlane16_swap_b32 v35, v34
	v_readlane_b32 s4, v253, 18
	s_waitcnt lgkmcnt(0)
	v_add_f32_e32 v34, v34, v35
	v_xor_b32_e32 v35, 32, v238
	v_cmp_lt_i32_e32 vcc, v35, v36
	s_nop 1
	v_cndmask_b32_e32 v35, v238, v35, vcc
	v_lshlrev_b32_e32 v35, 2, v35
	v_mov_b32_e32 v35, v34
	s_nop 1
	v_permlane32_swap_b32 v35, v34
	s_waitcnt lgkmcnt(0)
	v_add_f32_e32 v34, v34, v35
	v_fmamk_f32 v34, v34, 0x3c800000, v236
	v_rsq_f32_e32 v50, v34
	v_lshrrev_b32_e32 v34, 2, v74
	v_and_b32_e32 v34, 0x3f0, v34
	v_add_u32_e32 v34, v34, v177
	v_lshl_add_u32 v38, v34, 3, s4
	ds_read_b128 v[34:37], v38
	ds_read_b128 v[40:43], v38 offset:16
	v_mul_f32_e32 v38, v54, v50
	v_mul_f32_e32 v39, v55, v50
	v_mul_f32_e32 v44, v154, v50
	v_mul_f32_e32 v45, v155, v50
	v_mul_f32_e32 v38, v68, v38
	v_mul_f32_e32 v39, v69, v39
	v_mul_f32_e32 v44, v70, v44
	v_mul_f32_e32 v45, v71, v45
	s_waitcnt lgkmcnt(0)
	v_mov_b32_e32 v69, v36
	v_mov_b32_e32 v70, v34
	v_mov_b32_e32 v71, v37
	v_mov_b32_e32 v76, v36
	v_mov_b32_e32 v77, v34
	v_mov_b32_e32 v34, v37
	v_pk_mov_b32 v[36:37], v[44:45], v[38:39] op_sel:[1,0]
	v_mov_b32_e32 v68, v35
	v_mul_f32_e32 v70, v70, v38
	v_mul_f32_e32 v71, v71, v39
	v_mul_f32_e32 v34, v34, v36
	v_mul_f32_e32 v35, v35, v37
	v_mul_f32_e32 v36, v56, v50
	v_mul_f32_e32 v37, v57, v50
	v_pk_mov_b32 v[78:79], v[38:39], v[44:45] op_sel:[1,0]
	v_fma_f32 v38, v68, v44, v70
	v_fma_f32 v39, v69, v45, v71
	v_mul_f32_e32 v36, v64, v36
	v_mul_f32_e32 v37, v65, v37
	v_mov_b32_e32 v65, v42
	v_mov_b32_e32 v68, v42
	v_lshlrev_b32_e32 v42, 4, v75
	v_mul_f32_e32 v44, v152, v50
	v_mul_f32_e32 v45, v153, v50
	v_and_b32_e32 v42, 0x3f0, v42
	v_mul_f32_e32 v44, v66, v44
	v_mul_f32_e32 v45, v67, v45
	v_mov_b32_e32 v66, v40
	v_mov_b32_e32 v67, v43
	v_add_u32_e32 v42, v42, v177
	v_mov_b32_e32 v64, v41
	v_mul_f32_e32 v66, v66, v36
	v_mul_f32_e32 v67, v67, v37
	v_mov_b32_e32 v69, v40
	v_pk_mov_b32 v[70:71], v[36:37], v[44:45] op_sel:[1,0]
	v_mov_b32_e32 v40, v43
	v_pk_mov_b32 v[36:37], v[44:45], v[36:37] op_sel:[1,0]
	v_lshl_add_u32 v51, v42, 3, s4
	v_mul_f32_e32 v36, v40, v36
	v_mul_f32_e32 v37, v41, v37
	v_fma_f32 v40, v64, v44, v66
	v_fma_f32 v41, v65, v45, v67
	ds_read_b128 v[42:45], v51
	ds_read_b128 v[64:67], v51 offset:16
	v_fma_f32 v36, v68, v70, -v36
	v_fma_f32 v37, v69, v71, -v37
	v_mul_f32_e32 v68, v46, v50
	v_mul_f32_e32 v69, v47, v50
	v_fma_f32 v34, v76, v78, -v34
	v_fma_f32 v35, v77, v79, -v35
	v_mul_f32_e32 v60, v60, v68
	v_mul_f32_e32 v61, v61, v69
	v_mul_f32_e32 v68, v150, v50
	v_mul_f32_e32 v69, v151, v50
	s_waitcnt lgkmcnt(0)
	v_mov_b32_e32 v70, v42
	v_mul_f32_e32 v62, v62, v68
	v_mul_f32_e32 v63, v63, v69
	v_mov_b32_e32 v71, v45
	v_mov_b32_e32 v69, v44
	v_mul_f32_e32 v70, v70, v60
	v_mul_f32_e32 v71, v71, v61
	v_mov_b32_e32 v76, v44
	v_mov_b32_e32 v77, v42
	v_pk_mov_b32 v[78:79], v[60:61], v[62:63] op_sel:[1,0]
	v_mov_b32_e32 v42, v45
	v_pk_mov_b32 v[44:45], v[62:63], v[60:61] op_sel:[1,0]
	v_mul_f32_e32 v60, v48, v50
	v_mul_f32_e32 v61, v49, v50
	v_mul_f32_e32 v51, v149, v50
	v_mul_f32_e32 v50, v148, v50
	v_mov_b32_e32 v68, v43
	v_mul_f32_e32 v42, v42, v44
	v_mul_f32_e32 v43, v43, v45
	v_mul_f32_e32 v52, v52, v60
	v_mul_f32_e32 v53, v53, v61
	v_mul_f32_e32 v58, v58, v50
	v_mul_f32_e32 v59, v59, v51
	v_mov_b32_e32 v50, v64
	v_mov_b32_e32 v51, v67
	v_fma_f32 v44, v76, v78, -v42
	v_fma_f32 v45, v77, v79, -v43
	v_fma_f32 v42, v68, v62, v70
	v_fma_f32 v43, v69, v63, v71
	v_mul_f32_e32 v62, v50, v52
	v_mul_f32_e32 v63, v51, v53
	v_mov_b32_e32 v51, v64
	v_pk_mov_b32 v[68:69], v[52:53], v[58:59] op_sel:[1,0]
	v_mov_b32_e32 v64, v67
	v_pk_mov_b32 v[52:53], v[58:59], v[52:53] op_sel:[1,0]
	v_mov_b32_e32 v60, v65
	v_mov_b32_e32 v61, v66
	v_mov_b32_e32 v50, v66
	v_mul_f32_e32 v52, v64, v52
	v_mul_f32_e32 v53, v65, v53
	s_nop 0
	v_fma_f32 v50, v50, v68, -v52
	v_fma_f32 v51, v51, v69, -v53
	v_fma_f32 v52, v60, v58, v62
	v_fma_f32 v53, v61, v59, v63
	s_and_b64 vcc, exec, s[42:43]
	s_cbranch_vccz .LBB0_816
	s_branch .LBB0_817
.LBB0_815:
	v_mul_f32_e32 v38, v42, v72
	v_mul_f32_e32 v39, v43, v72
	v_mul_f32_e32 v40, v44, v72
	v_mul_f32_e32 v41, v45, v72
	v_mul_f32_e32 v42, v34, v72
	v_mul_f32_e32 v43, v35, v72
	v_mul_f32_e32 v52, v36, v72
	v_mul_f32_e32 v53, v37, v72
	v_pk_mov_b32 v[44:45], v[60:61], v[62:63] op_sel:[1,0]
	v_pk_mov_b32 v[36:37], v[64:65], v[66:67] op_sel:[1,0]
	v_pk_mov_b32 v[34:35], v[68:69], v[70:71] op_sel:[1,0]
	s_and_b64 vcc, exec, s[42:43]
	s_cbranch_vccnz .LBB0_817
.LBB0_816:
	v_mul_f32_e32 v34, s68, v34
	v_mul_f32_e32 v35, s68, v35
	v_mul_f32_e32 v36, s68, v36
	v_mul_f32_e32 v37, s68, v37
	v_mul_f32_e32 v38, s68, v38
	v_mul_f32_e32 v39, s68, v39
	v_mul_f32_e32 v40, s68, v40
	v_mul_f32_e32 v41, s68, v41
	v_mul_f32_e32 v44, s68, v44
	v_mul_f32_e32 v45, s68, v45
	v_mul_f32_e32 v50, s68, v50
	v_mul_f32_e32 v51, s68, v51
	v_mul_f32_e32 v42, s68, v42
	v_mul_f32_e32 v43, s68, v43
	v_mul_f32_e32 v52, s68, v52
	v_mul_f32_e32 v53, s68, v53

.LBB0_821:
	v_mov_b32_e32 v53, v175
	s_nop 0
	v_mov_b32_e32 v35, v29
	v_lshl_add_u32 v34, v53, 2, s97
	ds_read_b32 v52, v34 offset:640
	v_mov_b32_e32 v29, v25
	s_add_i32 s4, s94, 0xa0
	v_mov_b32_e32 v34, v24
	v_add_u32_e32 v59, s4, v53
	s_waitcnt lgkmcnt(0)
	v_mul_f32_e32 v50, v28, v52
	v_mul_f32_e32 v51, v29, v52
	v_mov_b32_e32 v28, v26
	v_mov_b32_e32 v29, v31
	v_mul_f32_e32 v40, v28, v52
	v_mul_f32_e32 v41, v29, v52
	v_mov_b32_e32 v29, v21
	v_mov_b32_e32 v21, v17
	v_mov_b32_e32 v31, v27
	v_mul_f32_e32 v38, v20, v52
	v_mul_f32_e32 v39, v21, v52
	v_mov_b32_e32 v20, v18
	v_mov_b32_e32 v21, v23
	v_mov_b32_e32 v23, v19
	v_mul_f32_e32 v44, v34, v52
	v_mul_f32_e32 v45, v35, v52
	v_mul_f32_e32 v42, v30, v52
	v_mul_f32_e32 v43, v31, v52
	v_mov_b32_e32 v28, v16
	v_mul_f32_e32 v30, v20, v52
	v_mul_f32_e32 v31, v21, v52
	v_mul_f32_e32 v34, v22, v52
	v_mul_f32_e32 v35, v23, v52
	v_add_u32_e32 v58, s66, v59
	v_mul_f32_e32 v36, v28, v52
	v_mul_f32_e32 v37, v29, v52
	s_and_b64 vcc, exec, s[40:41]
	v_pk_mov_b32 v[28:29], v[30:31], v[34:35] op_sel:[1,0]
	s_cbranch_vccnz .LBB0_823
	v_mul_f32_e32 v16, v50, v50
	v_mul_f32_e32 v17, v51, v51
	v_mul_f32_e32 v18, v44, v44
	v_mul_f32_e32 v19, v45, v45
	v_mul_f32_e32 v20, v42, v42
	v_mul_f32_e32 v21, v43, v43
	v_add_f32_e32 v16, v16, v19
	v_mul_f32_e32 v22, v40, v40
	v_mul_f32_e32 v23, v41, v41
	v_add_f32_e32 v16, v20, v16
	v_add_f32_e32 v16, v23, v16
	v_add_f32_e32 v16, v18, v16
	v_add_f32_e32 v16, v17, v16
	v_add_f32_e32 v16, v22, v16
	v_add_f32_e32 v16, v21, v16
	v_fmac_f32_e32 v16, v38, v38
	v_mul_f32_e32 v24, v28, v28
	v_mul_f32_e32 v25, v29, v29
	v_fmac_f32_e32 v16, v37, v37
	v_pk_mov_b32 v[26:27], v[38:39], v[36:37] op_sel:[1,0]
	v_add_f32_e32 v16, v25, v16
	v_mul_f32_e32 v26, v26, v26
	v_mul_f32_e32 v27, v27, v27
	v_add_f32_e32 v16, v24, v16
	v_and_b32_e32 v18, 64, v238
	v_pk_mov_b32 v[28:29], v[34:35], v[30:31] op_sel:[1,0]
	v_add_f32_e32 v16, v27, v16
	v_xor_b32_e32 v17, 16, v238
	v_add_u32_e32 v18, 64, v18
	v_mul_f32_e32 v28, v28, v28
	v_mul_f32_e32 v29, v29, v29
	v_add_f32_e32 v16, v26, v16
	v_cmp_lt_i32_e32 vcc, v17, v18
	v_add_f32_e32 v16, v29, v16
	v_add_f32_e32 v16, v28, v16
	v_cndmask_b32_e32 v17, v238, v17, vcc
	v_lshlrev_b32_e32 v17, 2, v17
	v_mov_b32_e32 v17, v16
	s_nop 1
	v_permlane16_swap_b32 v17, v16
	v_readlane_b32 s4, v253, 18
	s_waitcnt lgkmcnt(0)
	v_add_f32_e32 v16, v16, v17
	v_xor_b32_e32 v17, 32, v238
	v_cmp_lt_i32_e32 vcc, v17, v18
	s_nop 1
	v_cndmask_b32_e32 v17, v238, v17, vcc
	v_lshlrev_b32_e32 v17, 2, v17
	v_mov_b32_e32 v17, v16
	s_nop 1
	v_permlane32_swap_b32 v17, v16
	s_waitcnt lgkmcnt(0)
	v_add_f32_e32 v16, v16, v17
	v_fmamk_f32 v16, v16, 0x3c800000, v236
	v_rsq_f32_e32 v28, v16
	v_lshrrev_b32_e32 v16, 2, v58
	v_and_b32_e32 v16, 0x3f0, v16
	v_add_u32_e32 v16, v16, v177
	v_lshl_add_u32 v20, v16, 3, s4
	ds_read_b128 v[16:19], v20
	ds_read_b128 v[22:25], v20 offset:16
	v_mul_f32_e32 v20, v54, v28
	v_mul_f32_e32 v21, v55, v28
	v_mul_f32_e32 v26, v154, v28
	v_mul_f32_e32 v27, v155, v28
	v_mul_f32_e32 v20, v44, v20
	v_mul_f32_e32 v21, v45, v21
	v_mul_f32_e32 v26, v50, v26
	v_mul_f32_e32 v27, v51, v27
	s_waitcnt lgkmcnt(0)
	v_mov_b32_e32 v45, v18
	v_mov_b32_e32 v50, v16
	v_mov_b32_e32 v51, v19
	v_mov_b32_e32 v60, v18
	v_mov_b32_e32 v61, v16
	v_mov_b32_e32 v16, v19
	v_pk_mov_b32 v[18:19], v[26:27], v[20:21] op_sel:[1,0]
	v_mov_b32_e32 v44, v17
	v_mul_f32_e32 v50, v50, v20
	v_mul_f32_e32 v51, v51, v21
	v_mul_f32_e32 v16, v16, v18
	v_mul_f32_e32 v17, v17, v19
	v_mul_f32_e32 v18, v56, v28
	v_mul_f32_e32 v19, v57, v28
	v_pk_mov_b32 v[62:63], v[20:21], v[26:27] op_sel:[1,0]
	v_fma_f32 v20, v44, v26, v50
	v_fma_f32 v21, v45, v27, v51
	v_mul_f32_e32 v18, v40, v18
	v_mul_f32_e32 v19, v41, v19
	v_mov_b32_e32 v41, v24
	v_mov_b32_e32 v44, v24
	v_lshlrev_b32_e32 v24, 4, v59
	v_mul_f32_e32 v26, v152, v28
	v_mul_f32_e32 v27, v153, v28
	v_and_b32_e32 v24, 0x3f0, v24
	v_mul_f32_e32 v26, v42, v26
	v_mul_f32_e32 v27, v43, v27
	v_mov_b32_e32 v42, v22
	v_mov_b32_e32 v43, v25
	v_add_u32_e32 v24, v24, v177
	v_mov_b32_e32 v40, v23
	v_mul_f32_e32 v42, v42, v18
	v_mul_f32_e32 v43, v43, v19
	v_mov_b32_e32 v45, v22
	v_pk_mov_b32 v[50:51], v[18:19], v[26:27] op_sel:[1,0]
	v_mov_b32_e32 v22, v25
	v_pk_mov_b32 v[18:19], v[26:27], v[18:19] op_sel:[1,0]
	v_lshl_add_u32 v29, v24, 3, s4
	v_mul_f32_e32 v18, v22, v18
	v_mul_f32_e32 v19, v23, v19
	v_fma_f32 v22, v40, v26, v42
	v_fma_f32 v23, v41, v27, v43
	ds_read_b128 v[24:27], v29
	ds_read_b128 v[40:43], v29 offset:16
	v_fma_f32 v18, v44, v50, -v18
	v_fma_f32 v19, v45, v51, -v19
	v_mul_f32_e32 v44, v46, v28
	v_mul_f32_e32 v45, v47, v28
	v_fma_f32 v16, v60, v62, -v16
	v_fma_f32 v17, v61, v63, -v17
	v_mul_f32_e32 v36, v36, v44
	v_mul_f32_e32 v37, v37, v45
	v_mul_f32_e32 v44, v150, v28
	v_mul_f32_e32 v45, v151, v28
	s_waitcnt lgkmcnt(0)
	v_mov_b32_e32 v50, v24
	v_mul_f32_e32 v38, v38, v44
	v_mul_f32_e32 v39, v39, v45
	v_mov_b32_e32 v51, v27
	v_mov_b32_e32 v45, v26
	v_mul_f32_e32 v50, v50, v36
	v_mul_f32_e32 v51, v51, v37
	v_mov_b32_e32 v60, v26
	v_mov_b32_e32 v61, v24
	v_pk_mov_b32 v[62:63], v[36:37], v[38:39] op_sel:[1,0]
	v_mov_b32_e32 v24, v27
	v_pk_mov_b32 v[26:27], v[38:39], v[36:37] op_sel:[1,0]
	v_mul_f32_e32 v36, v48, v28
	v_mul_f32_e32 v37, v49, v28
	v_mul_f32_e32 v29, v149, v28
	v_mul_f32_e32 v28, v148, v28
	v_mov_b32_e32 v44, v25
	v_mul_f32_e32 v24, v24, v26
	v_mul_f32_e32 v25, v25, v27
	v_mul_f32_e32 v30, v30, v36
	v_mul_f32_e32 v31, v31, v37
	v_mul_f32_e32 v34, v34, v28
	v_mul_f32_e32 v35, v35, v29
	v_mov_b32_e32 v28, v40
	v_mov_b32_e32 v29, v43
	v_fma_f32 v26, v60, v62, -v24
	v_fma_f32 v27, v61, v63, -v25
	v_fma_f32 v24, v44, v38, v50
	v_fma_f32 v25, v45, v39, v51
	v_mul_f32_e32 v38, v28, v30
	v_mul_f32_e32 v39, v29, v31
	v_mov_b32_e32 v29, v40
	v_pk_mov_b32 v[44:45], v[30:31], v[34:35] op_sel:[1,0]
	v_mov_b32_e32 v40, v43
	v_pk_mov_b32 v[30:31], v[34:35], v[30:31] op_sel:[1,0]
	v_mov_b32_e32 v36, v41
	v_mov_b32_e32 v37, v42
	v_mov_b32_e32 v28, v42
	v_mul_f32_e32 v30, v40, v30
	v_mul_f32_e32 v31, v41, v31
	s_nop 0
	v_fma_f32 v28, v28, v44, -v30
	v_fma_f32 v29, v29, v45, -v31
	v_fma_f32 v30, v36, v34, v38
	v_fma_f32 v31, v37, v35, v39
	s_and_b64 vcc, exec, s[42:43]
	s_cbranch_vccz .LBB0_824
	s_branch .LBB0_825
.LBB0_823:
	v_mul_f32_e32 v20, v24, v52
	v_mul_f32_e32 v21, v25, v52
	v_mul_f32_e32 v22, v26, v52
	v_mul_f32_e32 v23, v27, v52
	v_mul_f32_e32 v24, v16, v52
	v_mul_f32_e32 v25, v17, v52
	v_mul_f32_e32 v30, v18, v52
	v_mul_f32_e32 v31, v19, v52
	v_pk_mov_b32 v[26:27], v[36:37], v[38:39] op_sel:[1,0]
	v_pk_mov_b32 v[18:19], v[40:41], v[42:43] op_sel:[1,0]
	v_pk_mov_b32 v[16:17], v[44:45], v[50:51] op_sel:[1,0]
	s_and_b64 vcc, exec, s[42:43]
	s_cbranch_vccnz .LBB0_825
.LBB0_824:
	v_mul_f32_e32 v16, s68, v16
	v_mul_f32_e32 v17, s68, v17
	v_mul_f32_e32 v18, s68, v18
	v_mul_f32_e32 v19, s68, v19
	v_mul_f32_e32 v20, s68, v20
	v_mul_f32_e32 v21, s68, v21
	v_mul_f32_e32 v22, s68, v22
	v_mul_f32_e32 v23, s68, v23
	v_mul_f32_e32 v26, s68, v26
	v_mul_f32_e32 v27, s68, v27
	v_mul_f32_e32 v28, s68, v28
	v_mul_f32_e32 v29, s68, v29
	v_mul_f32_e32 v24, s68, v24
	v_mul_f32_e32 v25, s68, v25
	v_mul_f32_e32 v30, s68, v30
	v_mul_f32_e32 v31, s68, v31

.LBB0_829:
	s_addk_i32 s94, 0xb0
	s_nop 0
	v_lshl_add_u32 v16, v175, 2, s97
	ds_read_b32 v30, v16 offset:704
	v_add_u32_e32 v34, s94, v175
	v_add_u32_e32 v31, s66, v34
	v_mov_b32_e32 v17, v13
	v_mov_b32_e32 v13, v9
	s_waitcnt lgkmcnt(0)
	v_mul_f32_e32 v28, v12, v30
	v_mul_f32_e32 v29, v13, v30
	v_mov_b32_e32 v12, v10
	v_mov_b32_e32 v13, v15
	v_mul_f32_e32 v22, v12, v30
	v_mul_f32_e32 v23, v13, v30
	v_mov_b32_e32 v13, v5
	v_mov_b32_e32 v5, v1
	v_mov_b32_e32 v16, v8
	v_mov_b32_e32 v15, v11
	v_mul_f32_e32 v20, v4, v30
	v_mul_f32_e32 v21, v5, v30
	v_mov_b32_e32 v4, v2
	v_mov_b32_e32 v5, v7
	v_mov_b32_e32 v7, v3
	v_mul_f32_e32 v26, v16, v30
	v_mul_f32_e32 v27, v17, v30
	v_mul_f32_e32 v24, v14, v30
	v_mul_f32_e32 v25, v15, v30
	v_mov_b32_e32 v12, v0
	v_mul_f32_e32 v14, v4, v30
	v_mul_f32_e32 v15, v5, v30
	v_mul_f32_e32 v16, v6, v30
	v_mul_f32_e32 v17, v7, v30
	v_mul_f32_e32 v18, v12, v30
	v_mul_f32_e32 v19, v13, v30
	s_and_b64 vcc, exec, s[40:41]
	v_pk_mov_b32 v[12:13], v[14:15], v[16:17] op_sel:[1,0]
	s_cbranch_vccnz .LBB0_831
	v_mul_f32_e32 v0, v28, v28
	v_mul_f32_e32 v1, v29, v29
	v_mul_f32_e32 v2, v26, v26
	v_mul_f32_e32 v3, v27, v27
	v_mul_f32_e32 v4, v24, v24
	v_mul_f32_e32 v5, v25, v25
	v_add_f32_e32 v0, v0, v3
	v_mul_f32_e32 v6, v22, v22
	v_mul_f32_e32 v7, v23, v23
	v_add_f32_e32 v0, v4, v0
	v_add_f32_e32 v0, v7, v0
	v_add_f32_e32 v0, v2, v0
	v_add_f32_e32 v0, v1, v0
	v_add_f32_e32 v0, v6, v0
	v_add_f32_e32 v0, v5, v0
	v_fmac_f32_e32 v0, v20, v20
	v_mul_f32_e32 v8, v12, v12
	v_mul_f32_e32 v9, v13, v13
	v_fmac_f32_e32 v0, v19, v19
	v_pk_mov_b32 v[10:11], v[20:21], v[18:19] op_sel:[1,0]
	v_add_f32_e32 v0, v9, v0
	v_mul_f32_e32 v10, v10, v10
	v_mul_f32_e32 v11, v11, v11
	v_add_f32_e32 v0, v8, v0
	v_and_b32_e32 v2, 64, v238
	v_pk_mov_b32 v[12:13], v[16:17], v[14:15] op_sel:[1,0]
	v_add_f32_e32 v0, v11, v0
	v_xor_b32_e32 v1, 16, v238
	v_add_u32_e32 v2, 64, v2
	v_mul_f32_e32 v12, v12, v12
	v_mul_f32_e32 v13, v13, v13
	v_add_f32_e32 v0, v10, v0
	v_cmp_lt_i32_e32 vcc, v1, v2
	v_add_f32_e32 v0, v13, v0
	v_add_f32_e32 v0, v12, v0
	v_cndmask_b32_e32 v1, v238, v1, vcc
	v_lshlrev_b32_e32 v1, 2, v1
	v_mov_b32_e32 v1, v0
	s_nop 1
	v_permlane16_swap_b32 v1, v0
	v_readlane_b32 s4, v253, 18
	s_waitcnt lgkmcnt(0)
	v_add_f32_e32 v0, v0, v1
	v_xor_b32_e32 v1, 32, v238
	v_cmp_lt_i32_e32 vcc, v1, v2
	s_nop 1
	v_cndmask_b32_e32 v1, v238, v1, vcc
	v_lshlrev_b32_e32 v1, 2, v1
	v_mov_b32_e32 v1, v0
	s_nop 1
	v_permlane32_swap_b32 v1, v0
	s_waitcnt lgkmcnt(0)
	v_add_f32_e32 v0, v0, v1
	v_fmamk_f32 v0, v0, 0x3c800000, v236
	v_rsq_f32_e32 v12, v0
	v_lshrrev_b32_e32 v0, 2, v31
	v_and_b32_e32 v0, 0x3f0, v0
	v_add_u32_e32 v0, v0, v177
	v_lshl_add_u32 v4, v0, 3, s4
	ds_read_b128 v[0:3], v4
	ds_read_b128 v[6:9], v4 offset:16
	v_mul_f32_e32 v4, v54, v12
	v_mul_f32_e32 v5, v55, v12
	v_mul_f32_e32 v10, v154, v12
	v_mul_f32_e32 v11, v155, v12
	v_mul_f32_e32 v4, v26, v4
	v_mul_f32_e32 v5, v27, v5
	v_mul_f32_e32 v10, v28, v10
	v_mul_f32_e32 v11, v29, v11
	s_waitcnt lgkmcnt(0)
	v_mov_b32_e32 v27, v2
	v_mov_b32_e32 v28, v0
	v_mov_b32_e32 v29, v3
	v_mov_b32_e32 v36, v2
	v_mov_b32_e32 v37, v0
	v_mov_b32_e32 v0, v3
	v_pk_mov_b32 v[2:3], v[10:11], v[4:5] op_sel:[1,0]
	v_mov_b32_e32 v26, v1
	v_mul_f32_e32 v28, v28, v4
	v_mul_f32_e32 v29, v29, v5
	v_mul_f32_e32 v0, v0, v2
	v_mul_f32_e32 v1, v1, v3
	v_mul_f32_e32 v2, v56, v12
	v_mul_f32_e32 v3, v57, v12
	v_pk_mov_b32 v[38:39], v[4:5], v[10:11] op_sel:[1,0]
	v_fma_f32 v4, v26, v10, v28
	v_fma_f32 v5, v27, v11, v29
	v_mul_f32_e32 v2, v22, v2
	v_mul_f32_e32 v3, v23, v3
	v_mov_b32_e32 v23, v8
	v_mov_b32_e32 v26, v8
	v_lshlrev_b32_e32 v8, 4, v34
	v_mul_f32_e32 v10, v152, v12
	v_mul_f32_e32 v11, v153, v12
	v_and_b32_e32 v8, 0x3f0, v8
	v_mul_f32_e32 v10, v24, v10
	v_mul_f32_e32 v11, v25, v11
	v_mov_b32_e32 v24, v6
	v_mov_b32_e32 v25, v9
	v_add_u32_e32 v8, v8, v177
	v_mov_b32_e32 v22, v7
	v_mul_f32_e32 v24, v24, v2
	v_mul_f32_e32 v25, v25, v3
	v_mov_b32_e32 v27, v6
	v_pk_mov_b32 v[28:29], v[2:3], v[10:11] op_sel:[1,0]
	v_mov_b32_e32 v6, v9
	v_pk_mov_b32 v[2:3], v[10:11], v[2:3] op_sel:[1,0]
	v_lshl_add_u32 v13, v8, 3, s4
	v_mul_f32_e32 v2, v6, v2
	v_mul_f32_e32 v3, v7, v3
	v_fma_f32 v6, v22, v10, v24
	v_fma_f32 v7, v23, v11, v25
	ds_read_b128 v[8:11], v13
	ds_read_b128 v[22:25], v13 offset:16
	v_fma_f32 v2, v26, v28, -v2
	v_fma_f32 v3, v27, v29, -v3
	v_mul_f32_e32 v26, v46, v12
	v_mul_f32_e32 v27, v47, v12
	v_fma_f32 v0, v36, v38, -v0
	v_fma_f32 v1, v37, v39, -v1
	v_mul_f32_e32 v18, v18, v26
	v_mul_f32_e32 v19, v19, v27
	v_mul_f32_e32 v26, v150, v12
	v_mul_f32_e32 v27, v151, v12
	s_waitcnt lgkmcnt(0)
	v_mov_b32_e32 v28, v8
	v_mul_f32_e32 v20, v20, v26
	v_mul_f32_e32 v21, v21, v27
	v_mov_b32_e32 v29, v11
	v_mov_b32_e32 v27, v10
	v_mul_f32_e32 v28, v28, v18
	v_mul_f32_e32 v29, v29, v19
	v_mov_b32_e32 v34, v10
	v_mov_b32_e32 v35, v8
	v_pk_mov_b32 v[36:37], v[18:19], v[20:21] op_sel:[1,0]
	v_mov_b32_e32 v8, v11
	v_pk_mov_b32 v[10:11], v[20:21], v[18:19] op_sel:[1,0]
	v_mul_f32_e32 v18, v48, v12
	v_mul_f32_e32 v19, v49, v12
	v_mul_f32_e32 v13, v149, v12
	v_mul_f32_e32 v12, v148, v12
	v_mov_b32_e32 v26, v9
	v_mul_f32_e32 v8, v8, v10
	v_mul_f32_e32 v9, v9, v11
	v_mul_f32_e32 v14, v14, v18
	v_mul_f32_e32 v15, v15, v19
	v_mul_f32_e32 v16, v16, v12
	v_mul_f32_e32 v17, v17, v13
	v_mov_b32_e32 v12, v22
	v_mov_b32_e32 v13, v25
	v_fma_f32 v10, v34, v36, -v8
	v_fma_f32 v11, v35, v37, -v9
	v_fma_f32 v8, v26, v20, v28
	v_fma_f32 v9, v27, v21, v29
	v_mul_f32_e32 v20, v12, v14
	v_mul_f32_e32 v21, v13, v15
	v_mov_b32_e32 v13, v22
	v_pk_mov_b32 v[26:27], v[14:15], v[16:17] op_sel:[1,0]
	v_mov_b32_e32 v22, v25
	v_pk_mov_b32 v[14:15], v[16:17], v[14:15] op_sel:[1,0]
	v_mov_b32_e32 v18, v23
	v_mov_b32_e32 v19, v24
	v_mov_b32_e32 v12, v24
	v_mul_f32_e32 v14, v22, v14
	v_mul_f32_e32 v15, v23, v15
	s_nop 0
	v_fma_f32 v12, v12, v26, -v14
	v_fma_f32 v13, v13, v27, -v15
	v_fma_f32 v14, v18, v16, v20
	v_fma_f32 v15, v19, v17, v21
	s_and_b64 vcc, exec, s[42:43]
	s_cbranch_vccz .LBB0_832
	s_branch .LBB0_833
.LBB0_831:
	v_mul_f32_e32 v4, v8, v30
	v_mul_f32_e32 v5, v9, v30
	v_mul_f32_e32 v6, v10, v30
	v_mul_f32_e32 v7, v11, v30
	v_mul_f32_e32 v8, v0, v30
	v_mul_f32_e32 v9, v1, v30
	v_mul_f32_e32 v14, v2, v30
	v_mul_f32_e32 v15, v3, v30
	v_pk_mov_b32 v[10:11], v[18:19], v[20:21] op_sel:[1,0]
	v_pk_mov_b32 v[2:3], v[22:23], v[24:25] op_sel:[1,0]
	v_pk_mov_b32 v[0:1], v[26:27], v[28:29] op_sel:[1,0]
	s_and_b64 vcc, exec, s[42:43]
	s_cbranch_vccnz .LBB0_833
.LBB0_832:
	v_mul_f32_e32 v0, s68, v0
	v_mul_f32_e32 v1, s68, v1
	v_mul_f32_e32 v2, s68, v2
	v_mul_f32_e32 v3, s68, v3
	v_mul_f32_e32 v4, s68, v4
	v_mul_f32_e32 v5, s68, v5
	v_mul_f32_e32 v6, s68, v6
	v_mul_f32_e32 v7, s68, v7
	v_mul_f32_e32 v10, s68, v10
	v_mul_f32_e32 v11, s68, v11
	v_mul_f32_e32 v12, s68, v12
	v_mul_f32_e32 v13, s68, v13
	v_mul_f32_e32 v8, s68, v8
	v_mul_f32_e32 v9, s68, v9
	v_mul_f32_e32 v14, s68, v14
	v_mul_f32_e32 v15, s68, v15

.LBB0_1088:
	s_lshl_b32 s0, s5, 8
	v_mov_b32_e32 v32, v155
	v_mov_b32_e32 v130, v154
	s_add_i32 s0, s0, s93
	s_lshl_b32 s82, s4, 2
	v_add_u32_e32 v150, s0, v32
	s_lshl_b32 s0, s4, 9
	s_or_b32 s0, s0, s94
	v_lshlrev_b32_e32 v32, 11, v150
	v_lshlrev_b32_e32 v131, 4, v130
	v_add3_u32 v158, s0, v131, v32
	global_load_dwordx4 v[160:163], v158, s[52:53]
	v_add_u32_e32 v151, 0x100, v158
	global_load_dwordx4 v[164:167], v151, s[52:53]
	v_add_u32_e32 v32, 0x8000, v158
	v_add_u32_e32 v152, 0x8100, v158
	v_cmp_eq_u32_e32 vcc, 0, v130
	global_load_dwordx4 v[134:137], v32, s[52:53]
	global_load_dwordx4 v[130:133], v152, s[52:53]
	v_add_u32_e32 v168, 0x10000, v158
	global_load_dwordx4 v[172:175], v168, s[52:53]
	v_add_u32_e32 v169, 0x10100, v158
	global_load_dwordx4 v[176:179], v169, s[52:53]
	v_add_u32_e32 v168, 0x18000, v158
	global_load_dwordx4 v[180:183], v168, s[52:53]
	v_add_u32_e32 v169, 0x18100, v158
	global_load_dwordx4 v[186:189], v169, s[52:53]
	v_add_u32_e32 v168, 0x40000, v158
	global_load_dwordx4 v[190:193], v168, s[52:53]
	v_add_u32_e32 v169, 0x40100, v158
	global_load_dwordx4 v[202:205], v169, s[52:53]
	v_add_u32_e32 v168, 0x48000, v158
	global_load_dwordx4 v[206:209], v168, s[52:53]
	v_add_u32_e32 v169, 0x48100, v158
	global_load_dwordx4 v[210:213], v169, s[52:53]
	v_add_u32_e32 v168, 0x50000, v158
	global_load_dwordx4 v[214:217], v168, s[52:53]
	v_add_u32_e32 v169, 0x50100, v158
	global_load_dwordx4 v[218:221], v169, s[52:53]
	s_ashr_i32 s83, s82, 31
	s_waitcnt vmcnt(12)
	v_lshlrev_b32_e32 v168, 16, v160
	v_and_b32_e32 v169, 0xffff0000, v160
	v_lshlrev_b32_e32 v160, 16, v161
	v_and_b32_e32 v161, 0xffff0000, v161
	v_lshlrev_b32_e32 v170, 16, v162
	v_and_b32_e32 v171, 0xffff0000, v162
	v_lshlrev_b32_e32 v162, 16, v163
	v_and_b32_e32 v163, 0xffff0000, v163
	v_add_f32_e32 v128, v128, v160
	v_add_f32_e32 v129, v129, v161
	v_add_f32_e32 v126, v126, v168
	v_add_f32_e32 v127, v127, v169
	v_add_f32_e32 v160, v124, v162
	v_add_f32_e32 v161, v125, v163
	v_add_f32_e32 v162, v122, v170
	v_add_f32_e32 v163, v123, v171
	v_cvt_pk_bf16_f32 v122, v126, v127
	v_cvt_pk_bf16_f32 v123, v128, v129
	s_nop 0
	v_cvt_pk_bf16_f32 v124, v162, v163
	v_cvt_pk_bf16_f32 v125, v160, v161
	global_store_dwordx4 v158, v[122:125], s[52:53]
	s_nop 1
	v_mul_f32_e32 v122, v127, v127
	v_mul_f32_e32 v123, v129, v129
	v_fmac_f32_e32 v122, v126, v126
	v_fmac_f32_e32 v123, v128, v128
	v_add_f32_e32 v122, v122, v123
	v_mul_f32_e32 v123, v163, v163
	v_fmac_f32_e32 v123, v162, v162
	v_add_f32_e32 v122, v123, v122
	v_mul_f32_e32 v123, v161, v161
	v_fmac_f32_e32 v123, v160, v160
	v_add_f32_e32 v153, v123, v122
	v_lshlrev_b32_e32 v122, 16, v164
	v_and_b32_e32 v123, 0xffff0000, v164
	v_lshlrev_b32_e32 v124, 16, v165
	v_and_b32_e32 v125, 0xffff0000, v165
	v_lshlrev_b32_e32 v126, 16, v166
	v_and_b32_e32 v127, 0xffff0000, v166
	v_lshlrev_b32_e32 v128, 16, v167
	v_and_b32_e32 v129, 0xffff0000, v167
	v_add_f32_e32 v120, v120, v124
	v_add_f32_e32 v121, v121, v125
	v_add_f32_e32 v118, v118, v122
	v_add_f32_e32 v119, v119, v123
	v_add_f32_e32 v124, v114, v126
	v_add_f32_e32 v125, v115, v127
	v_cvt_pk_bf16_f32 v114, v118, v119
	v_cvt_pk_bf16_f32 v115, v120, v121
	v_add_f32_e32 v122, v116, v128
	v_add_f32_e32 v123, v117, v129
	v_cvt_pk_bf16_f32 v116, v124, v125
	s_nop 0
	v_cvt_pk_bf16_f32 v117, v122, v123
	global_store_dwordx4 v151, v[114:117], s[52:53]
	s_nop 1
	v_mul_f32_e32 v114, v119, v119
	v_mul_f32_e32 v115, v121, v121
	v_fmac_f32_e32 v114, v118, v118
	v_fmac_f32_e32 v115, v120, v120
	v_add_f32_e32 v114, v114, v115
	v_mul_f32_e32 v115, v125, v125
	v_fmac_f32_e32 v115, v124, v124
	v_add_f32_e32 v114, v115, v114
	v_mul_f32_e32 v115, v123, v123
	v_fmac_f32_e32 v115, v122, v122
	v_and_b32_e32 v116, 64, v238
	v_add_f32_e32 v114, v115, v114
	v_xor_b32_e32 v115, 16, v238
	v_add_u32_e32 v116, 64, v116
	v_cmp_lt_i32_e64 s[0:1], v115, v116
	v_add_f32_e32 v114, v153, v114
	s_nop 0
	v_cndmask_b32_e64 v115, v238, v115, s[0:1]
	v_lshlrev_b32_e32 v124, 2, v115
	v_mov_b32_e32 v115, v114
	s_nop 1
	v_permlane16_swap_b32 v115, v114
	s_waitcnt lgkmcnt(0)
	v_add_f32_e32 v114, v114, v115
	v_xor_b32_e32 v115, 32, v238
	v_cmp_lt_i32_e64 s[0:1], v115, v116
	s_nop 1
	v_cndmask_b32_e64 v115, v238, v115, s[0:1]
	v_lshlrev_b32_e32 v125, 2, v115
	v_mov_b32_e32 v115, v114
	s_nop 1
	v_permlane32_swap_b32 v115, v114
	s_and_saveexec_b64 s[0:1], vcc
	s_cbranch_execz .LBB0_1090
	v_ashrrev_i32_e32 v151, 31, v150
	s_waitcnt lgkmcnt(0)
	v_add_f32_e32 v116, v114, v115
	v_lshlrev_b64 v[114:115], 6, v[150:151]
	v_lshl_add_u64 v[114:115], s[54:55], 0, v[114:115]
	v_lshl_add_u64 v[114:115], s[82:83], 2, v[114:115]
	s_lshl_b32 s16, s88, 2
	v_lshl_add_u64 v[114:115], v[114:115], 0, s[16:17]
	global_store_dword v[114:115], v116, off

.LBB0_1272:
	s_lshl_b32 s0, s5, 8
	v_mov_b32_e32 v32, v155
	v_mov_b32_e32 v130, v154
	s_add_i32 s0, s0, s87
	s_lshl_b32 s70, s4, 2
	v_add_u32_e32 v150, s0, v32
	s_lshl_b32 s0, s4, 9
	s_or_b32 s0, s0, s88
	v_lshlrev_b32_e32 v32, 11, v150
	v_lshlrev_b32_e32 v131, 4, v130
	v_add3_u32 v158, s0, v131, v32
	global_load_dwordx4 v[160:163], v158, s[42:43]
	v_add_u32_e32 v151, 0x100, v158
	global_load_dwordx4 v[164:167], v151, s[42:43]
	v_add_u32_e32 v32, 0x8000, v158
	v_add_u32_e32 v152, 0x8100, v158
	v_cmp_eq_u32_e32 vcc, 0, v130
	global_load_dwordx4 v[134:137], v32, s[42:43]
	global_load_dwordx4 v[130:133], v152, s[42:43]
	v_add_u32_e32 v168, 0x10000, v158
	global_load_dwordx4 v[172:175], v168, s[42:43]
	v_add_u32_e32 v169, 0x10100, v158
	global_load_dwordx4 v[176:179], v169, s[42:43]
	v_add_u32_e32 v168, 0x18000, v158
	global_load_dwordx4 v[180:183], v168, s[42:43]
	v_add_u32_e32 v169, 0x18100, v158
	global_load_dwordx4 v[186:189], v169, s[42:43]
	v_add_u32_e32 v168, 0x40000, v158
	global_load_dwordx4 v[190:193], v168, s[42:43]
	v_add_u32_e32 v169, 0x40100, v158
	global_load_dwordx4 v[202:205], v169, s[42:43]
	v_add_u32_e32 v168, 0x48000, v158
	global_load_dwordx4 v[206:209], v168, s[42:43]
	v_add_u32_e32 v169, 0x48100, v158
	global_load_dwordx4 v[210:213], v169, s[42:43]
	v_add_u32_e32 v168, 0x50000, v158
	global_load_dwordx4 v[214:217], v168, s[42:43]
	v_add_u32_e32 v169, 0x50100, v158
	global_load_dwordx4 v[218:221], v169, s[42:43]
	s_ashr_i32 s71, s70, 31
	s_waitcnt vmcnt(12)
	v_lshlrev_b32_e32 v168, 16, v160
	v_and_b32_e32 v169, 0xffff0000, v160
	v_lshlrev_b32_e32 v160, 16, v161
	v_and_b32_e32 v161, 0xffff0000, v161
	v_lshlrev_b32_e32 v170, 16, v162
	v_and_b32_e32 v171, 0xffff0000, v162
	v_lshlrev_b32_e32 v162, 16, v163
	v_and_b32_e32 v163, 0xffff0000, v163
	v_add_f32_e32 v128, v128, v160
	v_add_f32_e32 v129, v129, v161
	v_add_f32_e32 v126, v126, v168
	v_add_f32_e32 v127, v127, v169
	v_add_f32_e32 v160, v124, v162
	v_add_f32_e32 v161, v125, v163
	v_add_f32_e32 v162, v122, v170
	v_add_f32_e32 v163, v123, v171
	v_cvt_pk_bf16_f32 v122, v126, v127
	v_cvt_pk_bf16_f32 v123, v128, v129
	s_nop 0
	v_cvt_pk_bf16_f32 v124, v162, v163
	v_cvt_pk_bf16_f32 v125, v160, v161
	global_store_dwordx4 v158, v[122:125], s[42:43]
	s_nop 1
	v_mul_f32_e32 v122, v127, v127
	v_mul_f32_e32 v123, v129, v129
	v_fmac_f32_e32 v122, v126, v126
	v_fmac_f32_e32 v123, v128, v128
	v_add_f32_e32 v122, v122, v123
	v_mul_f32_e32 v123, v163, v163
	v_fmac_f32_e32 v123, v162, v162
	v_add_f32_e32 v122, v123, v122
	v_mul_f32_e32 v123, v161, v161
	v_fmac_f32_e32 v123, v160, v160
	v_add_f32_e32 v153, v123, v122
	v_lshlrev_b32_e32 v122, 16, v164
	v_and_b32_e32 v123, 0xffff0000, v164
	v_lshlrev_b32_e32 v124, 16, v165
	v_and_b32_e32 v125, 0xffff0000, v165
	v_lshlrev_b32_e32 v126, 16, v166
	v_and_b32_e32 v127, 0xffff0000, v166
	v_lshlrev_b32_e32 v128, 16, v167
	v_and_b32_e32 v129, 0xffff0000, v167
	v_add_f32_e32 v120, v120, v124
	v_add_f32_e32 v121, v121, v125
	v_add_f32_e32 v118, v118, v122
	v_add_f32_e32 v119, v119, v123
	v_add_f32_e32 v124, v114, v126
	v_add_f32_e32 v125, v115, v127
	v_cvt_pk_bf16_f32 v114, v118, v119
	v_cvt_pk_bf16_f32 v115, v120, v121
	v_add_f32_e32 v122, v116, v128
	v_add_f32_e32 v123, v117, v129
	v_cvt_pk_bf16_f32 v116, v124, v125
	s_nop 0
	v_cvt_pk_bf16_f32 v117, v122, v123
	global_store_dwordx4 v151, v[114:117], s[42:43]
	s_nop 1
	v_mul_f32_e32 v114, v119, v119
	v_mul_f32_e32 v115, v121, v121
	v_fmac_f32_e32 v114, v118, v118
	v_fmac_f32_e32 v115, v120, v120
	v_add_f32_e32 v114, v114, v115
	v_mul_f32_e32 v115, v125, v125
	v_fmac_f32_e32 v115, v124, v124
	v_add_f32_e32 v114, v115, v114
	v_mul_f32_e32 v115, v123, v123
	v_fmac_f32_e32 v115, v122, v122
	v_and_b32_e32 v116, 64, v238
	v_add_f32_e32 v114, v115, v114
	v_xor_b32_e32 v115, 16, v238
	v_add_u32_e32 v116, 64, v116
	v_cmp_lt_i32_e64 s[0:1], v115, v116
	v_add_f32_e32 v114, v153, v114
	s_nop 0
	v_cndmask_b32_e64 v115, v238, v115, s[0:1]
	v_lshlrev_b32_e32 v124, 2, v115
	v_mov_b32_e32 v115, v114
	s_nop 1
	v_permlane16_swap_b32 v115, v114
	s_waitcnt lgkmcnt(0)
	v_add_f32_e32 v114, v114, v115
	v_xor_b32_e32 v115, 32, v238
	v_cmp_lt_i32_e64 s[0:1], v115, v116
	s_nop 1
	v_cndmask_b32_e64 v115, v238, v115, s[0:1]
	v_lshlrev_b32_e32 v125, 2, v115
	v_mov_b32_e32 v115, v114
	s_nop 1
	v_permlane32_swap_b32 v115, v114
	s_and_saveexec_b64 s[0:1], vcc
	s_cbranch_execz .LBB0_1274
	v_ashrrev_i32_e32 v151, 31, v150
	s_waitcnt lgkmcnt(0)
	v_add_f32_e32 v116, v114, v115
	v_lshlrev_b64 v[114:115], 6, v[150:151]
	v_lshl_add_u64 v[114:115], s[44:45], 0, v[114:115]
	v_lshl_add_u64 v[114:115], s[70:71], 2, v[114:115]
	s_lshl_b32 s16, s86, 2
	v_lshl_add_u64 v[114:115], v[114:115], 0, s[16:17]
	global_store_dword v[114:115], v116, off
